# GEMM phases: per-segment s_setprio toggling replaced by one static priority raise for waves 4-7 (set at kernel entry, restored after each attention pass)
# speedup vs baseline: 1.0105x; 1.0036x over previous
_Z13mla_hgrn2_fwd6Params:
	s_load_dwordx2 s[64:65], s[0:1], 0x108
	s_load_dwordx4 s[56:59], s[0:1], 0x78
	s_add_u32 s10, s0, 0x108
	s_addc_u32 s11, s1, 0
	v_mov_b32_e32 v1, 0
	s_waitcnt lgkmcnt(0)
	s_cmp_lt_u32 s2, s64
	s_cselect_b32 s3, 12, 18
	s_add_u32 s4, s10, s3
	s_addc_u32 s5, s11, 0
	global_load_ushort v2, v1, s[4:5]
	v_and_b32_e32 v184, 0x3ff, v0
	v_cmp_eq_u32_e64 s[78:79], 0, v184
	v_readfirstlane_b32 s99, v184
	s_cmp_lt_u32 s99, 0x100
	s_cbranch_scc1 .Lgp_entry
	s_setprio 1
.Lgp_entry:
	s_waitcnt vmcnt(0)
	v_readfirstlane_b32 s46, v2
	s_and_saveexec_b64 s[4:5], s[78:79]
	s_cbranch_execz .LBB0_2
	s_add_i32 s3, 0, 0x20000
	v_mov_b32_e32 v2, s3
	s_add_i32 s3, 0, 0x20004
	ds_write_b32 v2, v1
	v_mov_b32_e32 v2, s3
	s_add_i32 s3, 0, 0x20008
	ds_write_b32 v2, v1
	v_mov_b32_e32 v2, s3
	s_add_i32 s3, 0, 0x2000c
	ds_write_b32 v2, v1
	v_mov_b32_e32 v2, s3
	ds_write_b32 v2, v1

.LBB0_127:
	ds_read_b128 v[176:179], v167
	ds_read_b128 v[180:183], v167 offset:1024
	ds_read_b128 v[186:189], v167 offset:2048
	ds_read_b128 v[190:193], v167 offset:3072
	s_add_u32 s40, s38, 0xfff00080
	s_addc_u32 s41, s39, -1
	s_cmp_eq_u32 s54, 60
	s_cselect_b32 s43, s6, s41
	s_cselect_b32 s42, s7, s40
	s_cselect_b32 s41, s9, s29
	s_cselect_b32 s40, s11, s27
	v_lshl_add_u64 v[156:157], s[38:39], 0, v[138:139]
	s_add_i32 m0, s44, 0xc000
	ds_read_b128 v[194:197], v168
	ds_read_b128 v[198:201], v168 offset:1024
	ds_read_b128 v[202:205], v168 offset:2048
	ds_read_b128 v[206:209], v168 offset:3072
	ds_read_b128 v[210:213], v168 offset:4096
	ds_read_b128 v[214:217], v168 offset:5120
	ds_read_b128 v[218:221], v168 offset:6144
	ds_read_b128 v[222:225], v168 offset:7168
	global_load_lds_dwordx4 v[156:157], off
	v_lshl_add_u64 v[156:157], s[38:39], 0, v[140:141]
	s_add_i32 m0, s44, 0xe000
	s_nop 0
	global_load_lds_dwordx4 v[156:157], off
	s_waitcnt lgkmcnt(8)
	s_barrier
	s_waitcnt lgkmcnt(0)
	s_waitcnt lgkmcnt(0)
	v_mfma_f32_16x16x32_bf16 v[124:127], v[176:179], v[194:197], v[124:127]
	v_mfma_f32_16x16x32_bf16 v[124:127], v[180:183], v[198:201], v[124:127]
	v_mfma_f32_16x16x32_bf16 v[120:123], v[186:189], v[194:197], v[120:123]
	v_mfma_f32_16x16x32_bf16 v[120:123], v[190:193], v[198:201], v[120:123]
	v_mfma_f32_16x16x32_bf16 v[108:111], v[176:179], v[202:205], v[108:111]
	v_mfma_f32_16x16x32_bf16 v[108:111], v[180:183], v[206:209], v[108:111]
	v_mfma_f32_16x16x32_bf16 v[104:107], v[186:189], v[202:205], v[104:107]
	v_mfma_f32_16x16x32_bf16 v[104:107], v[190:193], v[206:209], v[104:107]
	v_mfma_f32_16x16x32_bf16 v[92:95], v[176:179], v[210:213], v[92:95]
	v_mfma_f32_16x16x32_bf16 v[92:95], v[180:183], v[214:217], v[92:95]
	v_mfma_f32_16x16x32_bf16 v[88:91], v[186:189], v[210:213], v[88:91]
	v_mfma_f32_16x16x32_bf16 v[88:91], v[190:193], v[214:217], v[88:91]
	v_mfma_f32_16x16x32_bf16 v[76:79], v[176:179], v[218:221], v[76:79]
	v_mfma_f32_16x16x32_bf16 v[76:79], v[180:183], v[222:225], v[76:79]
	v_mfma_f32_16x16x32_bf16 v[72:75], v[186:189], v[218:221], v[72:75]
	v_mfma_f32_16x16x32_bf16 v[72:75], v[190:193], v[222:225], v[72:75]
	s_barrier
	s_add_i32 s55, s72, s5
	v_lshl_add_u64 v[156:157], s[40:41], 0, v[130:131]
	s_mov_b32 m0, s55
	ds_read_b128 v[226:229], v169
	ds_read_b128 v[230:233], v169 offset:1024
	ds_read_b128 v[234:237], v169 offset:2048
	ds_read_b128 v[238:241], v169 offset:3072
	global_load_lds_dwordx4 v[156:157], off
	v_lshl_add_u64 v[162:163], s[40:41], 0, v[134:135]
	s_add_i32 m0, s55, 0x2000
	s_nop 0
	global_load_lds_dwordx4 v[162:163], off
	s_barrier
	s_waitcnt lgkmcnt(0)
	s_waitcnt lgkmcnt(0)
	v_mfma_f32_16x16x32_bf16 v[116:119], v[226:229], v[194:197], v[116:119]
	v_mfma_f32_16x16x32_bf16 v[116:119], v[230:233], v[198:201], v[116:119]
	v_mfma_f32_16x16x32_bf16 v[112:115], v[234:237], v[194:197], v[112:115]
	v_mfma_f32_16x16x32_bf16 v[112:115], v[238:241], v[198:201], v[112:115]
	v_mfma_f32_16x16x32_bf16 v[100:103], v[226:229], v[202:205], v[100:103]
	v_mfma_f32_16x16x32_bf16 v[100:103], v[230:233], v[206:209], v[100:103]
	v_mfma_f32_16x16x32_bf16 v[96:99], v[234:237], v[202:205], v[96:99]
	v_mfma_f32_16x16x32_bf16 v[96:99], v[238:241], v[206:209], v[96:99]
	v_mfma_f32_16x16x32_bf16 v[84:87], v[226:229], v[210:213], v[84:87]
	v_mfma_f32_16x16x32_bf16 v[84:87], v[230:233], v[214:217], v[84:87]
	v_mfma_f32_16x16x32_bf16 v[80:83], v[234:237], v[210:213], v[80:83]
	v_mfma_f32_16x16x32_bf16 v[80:83], v[238:241], v[214:217], v[80:83]
	v_mfma_f32_16x16x32_bf16 v[68:71], v[226:229], v[218:221], v[68:71]
	v_mfma_f32_16x16x32_bf16 v[68:71], v[230:233], v[222:225], v[68:71]
	v_mfma_f32_16x16x32_bf16 v[64:67], v[234:237], v[218:221], v[64:67]
	v_mfma_f32_16x16x32_bf16 v[64:67], v[238:241], v[222:225], v[64:67]
	s_mov_b32 m0, s44
	v_lshl_add_u64 v[170:171], s[42:43], 0, v[128:129]
	s_barrier
	ds_read_b128 v[194:197], v168 offset:16384
	ds_read_b128 v[198:201], v168 offset:17408
	ds_read_b128 v[202:205], v168 offset:18432
	ds_read_b128 v[206:209], v168 offset:19456
	ds_read_b128 v[210:213], v168 offset:20480
	ds_read_b128 v[214:217], v168 offset:21504
	ds_read_b128 v[218:221], v168 offset:22528
	ds_read_b128 v[222:225], v168 offset:23552
	global_load_lds_dwordx4 v[170:171], off
	v_lshl_add_u64 v[242:243], s[42:43], 0, v[132:133]
	s_mov_b32 m0, s45
	s_nop 0
	global_load_lds_dwordx4 v[242:243], off
	s_barrier
	s_waitcnt lgkmcnt(0)
	s_waitcnt lgkmcnt(0)
	v_mfma_f32_16x16x32_bf16 v[60:63], v[176:179], v[194:197], v[60:63]
	v_mfma_f32_16x16x32_bf16 v[60:63], v[180:183], v[198:201], v[60:63]
	v_mfma_f32_16x16x32_bf16 v[56:59], v[186:189], v[194:197], v[56:59]
	v_mfma_f32_16x16x32_bf16 v[56:59], v[190:193], v[198:201], v[56:59]
	v_mfma_f32_16x16x32_bf16 v[44:47], v[176:179], v[202:205], v[44:47]
	v_mfma_f32_16x16x32_bf16 v[44:47], v[180:183], v[206:209], v[44:47]
	v_mfma_f32_16x16x32_bf16 v[40:43], v[186:189], v[202:205], v[40:43]
	v_mfma_f32_16x16x32_bf16 v[40:43], v[190:193], v[206:209], v[40:43]
	v_mfma_f32_16x16x32_bf16 v[28:31], v[176:179], v[210:213], v[28:31]
	v_mfma_f32_16x16x32_bf16 v[28:31], v[180:183], v[214:217], v[28:31]
	v_mfma_f32_16x16x32_bf16 v[24:27], v[186:189], v[210:213], v[24:27]
	v_mfma_f32_16x16x32_bf16 v[24:27], v[190:193], v[214:217], v[24:27]
	v_mfma_f32_16x16x32_bf16 v[12:15], v[176:179], v[218:221], v[12:15]
	v_mfma_f32_16x16x32_bf16 v[12:15], v[180:183], v[222:225], v[12:15]
	v_mfma_f32_16x16x32_bf16 v[8:11], v[186:189], v[218:221], v[8:11]
	v_mfma_f32_16x16x32_bf16 v[8:11], v[190:193], v[222:225], v[8:11]
	s_barrier
	s_add_u32 s62, s40, 0x100000
	s_addc_u32 s63, s41, 0
	s_add_i32 s55, s73, s5
	v_lshl_add_u64 v[176:177], s[62:63], 0, v[130:131]
	s_mov_b32 m0, s55
	s_nop 0
	global_load_lds_dwordx4 v[176:177], off
	v_lshl_add_u64 v[176:177], s[62:63], 0, v[134:135]
	s_add_i32 m0, s55, 0x2000
	s_nop 0
	global_load_lds_dwordx4 v[176:177], off
	s_waitcnt vmcnt(6)
	s_barrier
	v_mfma_f32_16x16x32_bf16 v[52:55], v[226:229], v[194:197], v[52:55]
	v_mfma_f32_16x16x32_bf16 v[52:55], v[230:233], v[198:201], v[52:55]
	v_mfma_f32_16x16x32_bf16 v[48:51], v[234:237], v[194:197], v[48:51]
	v_mfma_f32_16x16x32_bf16 v[48:51], v[238:241], v[198:201], v[48:51]
	v_mfma_f32_16x16x32_bf16 v[36:39], v[226:229], v[202:205], v[36:39]
	v_mfma_f32_16x16x32_bf16 v[36:39], v[230:233], v[206:209], v[36:39]
	v_mfma_f32_16x16x32_bf16 v[32:35], v[234:237], v[202:205], v[32:35]
	v_mfma_f32_16x16x32_bf16 v[32:35], v[238:241], v[206:209], v[32:35]
	v_mfma_f32_16x16x32_bf16 v[20:23], v[226:229], v[210:213], v[20:23]
	v_mfma_f32_16x16x32_bf16 v[20:23], v[230:233], v[214:217], v[20:23]
	v_mfma_f32_16x16x32_bf16 v[16:19], v[234:237], v[210:213], v[16:19]
	v_mfma_f32_16x16x32_bf16 v[16:19], v[238:241], v[214:217], v[16:19]
	v_mfma_f32_16x16x32_bf16 v[4:7], v[226:229], v[218:221], v[4:7]
	v_mfma_f32_16x16x32_bf16 v[4:7], v[230:233], v[222:225], v[4:7]
	v_mfma_f32_16x16x32_bf16 v[0:3], v[234:237], v[218:221], v[0:3]
	v_mfma_f32_16x16x32_bf16 v[0:3], v[238:241], v[222:225], v[0:3]
	s_add_i32 s55, 0, 0x18000
	v_add_u32_e32 v137, s55, v165
	s_barrier
	ds_read_b128 v[176:179], v137
	ds_read_b128 v[180:183], v137 offset:1024
	ds_read_b128 v[186:189], v137 offset:2048
	ds_read_b128 v[190:193], v137 offset:3072
	s_add_u32 s42, s42, 0x100000
	s_addc_u32 s43, s43, 0
	s_mov_b32 m0, s46
	v_lshl_add_u64 v[226:227], s[42:43], 0, v[128:129]
	ds_read_b128 v[194:197], v168 offset:32768
	ds_read_b128 v[198:201], v168 offset:33792
	ds_read_b128 v[202:205], v168 offset:34816
	ds_read_b128 v[206:209], v168 offset:35840
	ds_read_b128 v[210:213], v168 offset:36864
	ds_read_b128 v[214:217], v168 offset:37888
	ds_read_b128 v[218:221], v168 offset:38912
	ds_read_b128 v[222:225], v168 offset:39936
	global_load_lds_dwordx4 v[226:227], off
	v_lshl_add_u64 v[226:227], s[42:43], 0, v[132:133]
	s_mov_b32 m0, s47
	s_nop 0
	global_load_lds_dwordx4 v[226:227], off
	s_waitcnt lgkmcnt(8)
	s_barrier
	s_waitcnt lgkmcnt(0)
	s_waitcnt lgkmcnt(0)
	v_mfma_f32_16x16x32_bf16 v[124:127], v[176:179], v[194:197], v[124:127]
	v_mfma_f32_16x16x32_bf16 v[124:127], v[180:183], v[198:201], v[124:127]
	v_mfma_f32_16x16x32_bf16 v[120:123], v[186:189], v[194:197], v[120:123]
	v_mfma_f32_16x16x32_bf16 v[120:123], v[190:193], v[198:201], v[120:123]
	v_mfma_f32_16x16x32_bf16 v[108:111], v[176:179], v[202:205], v[108:111]
	v_mfma_f32_16x16x32_bf16 v[108:111], v[180:183], v[206:209], v[108:111]
	v_mfma_f32_16x16x32_bf16 v[104:107], v[186:189], v[202:205], v[104:107]
	v_mfma_f32_16x16x32_bf16 v[104:107], v[190:193], v[206:209], v[104:107]
	v_mfma_f32_16x16x32_bf16 v[92:95], v[176:179], v[210:213], v[92:95]
	v_mfma_f32_16x16x32_bf16 v[92:95], v[180:183], v[214:217], v[92:95]
	v_mfma_f32_16x16x32_bf16 v[88:91], v[186:189], v[210:213], v[88:91]
	v_mfma_f32_16x16x32_bf16 v[88:91], v[190:193], v[214:217], v[88:91]
	v_mfma_f32_16x16x32_bf16 v[76:79], v[176:179], v[218:221], v[76:79]
	v_mfma_f32_16x16x32_bf16 v[76:79], v[180:183], v[222:225], v[76:79]
	v_mfma_f32_16x16x32_bf16 v[72:75], v[186:189], v[218:221], v[72:75]
	v_mfma_f32_16x16x32_bf16 v[72:75], v[190:193], v[222:225], v[72:75]
	s_barrier
	s_add_i32 s42, 0, 0x1c000
	s_add_i32 s43, s55, s5
	v_add_u32_e32 v137, s42, v165
	v_lshl_add_u64 v[156:157], v[156:157], 0, s[24:25]
	s_mov_b32 m0, s43
	ds_read_b128 v[226:229], v137
	ds_read_b128 v[230:233], v137 offset:1024
	ds_read_b128 v[234:237], v137 offset:2048
	ds_read_b128 v[238:241], v137 offset:3072
	global_load_lds_dwordx4 v[156:157], off
	v_lshl_add_u64 v[156:157], v[162:163], 0, s[24:25]
	s_add_i32 m0, s43, 0x2000
	s_nop 0
	global_load_lds_dwordx4 v[156:157], off
	s_barrier
	s_waitcnt lgkmcnt(0)
	s_waitcnt lgkmcnt(0)
	v_mfma_f32_16x16x32_bf16 v[116:119], v[226:229], v[194:197], v[116:119]
	v_mfma_f32_16x16x32_bf16 v[116:119], v[230:233], v[198:201], v[116:119]
	v_mfma_f32_16x16x32_bf16 v[112:115], v[234:237], v[194:197], v[112:115]
	v_mfma_f32_16x16x32_bf16 v[112:115], v[238:241], v[198:201], v[112:115]
	v_mfma_f32_16x16x32_bf16 v[100:103], v[226:229], v[202:205], v[100:103]
	v_mfma_f32_16x16x32_bf16 v[100:103], v[230:233], v[206:209], v[100:103]
	v_mfma_f32_16x16x32_bf16 v[96:99], v[234:237], v[202:205], v[96:99]
	v_mfma_f32_16x16x32_bf16 v[96:99], v[238:241], v[206:209], v[96:99]
	v_mfma_f32_16x16x32_bf16 v[84:87], v[226:229], v[210:213], v[84:87]
	v_mfma_f32_16x16x32_bf16 v[84:87], v[230:233], v[214:217], v[84:87]
	v_mfma_f32_16x16x32_bf16 v[80:83], v[234:237], v[210:213], v[80:83]
	v_mfma_f32_16x16x32_bf16 v[80:83], v[238:241], v[214:217], v[80:83]
	v_mfma_f32_16x16x32_bf16 v[68:71], v[226:229], v[218:221], v[68:71]
	v_mfma_f32_16x16x32_bf16 v[68:71], v[230:233], v[222:225], v[68:71]
	v_mfma_f32_16x16x32_bf16 v[64:67], v[234:237], v[218:221], v[64:67]
	v_mfma_f32_16x16x32_bf16 v[64:67], v[238:241], v[222:225], v[64:67]
	s_mov_b32 m0, s49
	v_lshl_add_u64 v[156:157], v[170:171], 0, s[24:25]
	s_barrier
	ds_read_b128 v[194:197], v168 offset:49152
	ds_read_b128 v[198:201], v168 offset:50176
	ds_read_b128 v[202:205], v168 offset:51200
	ds_read_b128 v[206:209], v168 offset:52224
	ds_read_b128 v[210:213], v168 offset:53248
	ds_read_b128 v[214:217], v168 offset:54272
	ds_read_b128 v[218:221], v168 offset:55296
	ds_read_b128 v[222:225], v168 offset:56320
	global_load_lds_dwordx4 v[156:157], off
	v_lshl_add_u64 v[156:157], v[242:243], 0, s[24:25]
	s_mov_b32 m0, s50
	s_nop 0
	global_load_lds_dwordx4 v[156:157], off
	s_barrier
	s_waitcnt lgkmcnt(0)
	s_waitcnt lgkmcnt(0)
	v_mfma_f32_16x16x32_bf16 v[60:63], v[176:179], v[194:197], v[60:63]
	v_mfma_f32_16x16x32_bf16 v[60:63], v[180:183], v[198:201], v[60:63]
	v_mfma_f32_16x16x32_bf16 v[56:59], v[186:189], v[194:197], v[56:59]
	v_mfma_f32_16x16x32_bf16 v[56:59], v[190:193], v[198:201], v[56:59]
	v_mfma_f32_16x16x32_bf16 v[44:47], v[176:179], v[202:205], v[44:47]
	v_mfma_f32_16x16x32_bf16 v[44:47], v[180:183], v[206:209], v[44:47]
	v_mfma_f32_16x16x32_bf16 v[40:43], v[186:189], v[202:205], v[40:43]
	v_mfma_f32_16x16x32_bf16 v[40:43], v[190:193], v[206:209], v[40:43]
	v_mfma_f32_16x16x32_bf16 v[28:31], v[176:179], v[210:213], v[28:31]
	v_mfma_f32_16x16x32_bf16 v[28:31], v[180:183], v[214:217], v[28:31]
	v_mfma_f32_16x16x32_bf16 v[24:27], v[186:189], v[210:213], v[24:27]
	v_mfma_f32_16x16x32_bf16 v[24:27], v[190:193], v[214:217], v[24:27]
	v_mfma_f32_16x16x32_bf16 v[12:15], v[176:179], v[218:221], v[12:15]
	v_mfma_f32_16x16x32_bf16 v[12:15], v[180:183], v[222:225], v[12:15]
	v_mfma_f32_16x16x32_bf16 v[8:11], v[186:189], v[218:221], v[8:11]
	v_mfma_f32_16x16x32_bf16 v[8:11], v[190:193], v[222:225], v[8:11]
	s_barrier
	s_add_u32 s40, s40, 0x100080
	s_addc_u32 s41, s41, 0
	s_add_i32 s42, s42, s5
	v_lshl_add_u64 v[156:157], s[40:41], 0, v[130:131]
	s_mov_b32 m0, s42
	s_nop 0
	global_load_lds_dwordx4 v[156:157], off
	v_lshl_add_u64 v[156:157], s[40:41], 0, v[134:135]
	s_add_i32 m0, s42, 0x2000
	s_nop 0
	global_load_lds_dwordx4 v[156:157], off
	s_waitcnt vmcnt(6)
	s_barrier
	v_mfma_f32_16x16x32_bf16 v[52:55], v[226:229], v[194:197], v[52:55]
	v_mfma_f32_16x16x32_bf16 v[52:55], v[230:233], v[198:201], v[52:55]
	v_mfma_f32_16x16x32_bf16 v[48:51], v[234:237], v[194:197], v[48:51]
	v_mfma_f32_16x16x32_bf16 v[48:51], v[238:241], v[198:201], v[48:51]
	v_mfma_f32_16x16x32_bf16 v[36:39], v[226:229], v[202:205], v[36:39]
	v_mfma_f32_16x16x32_bf16 v[36:39], v[230:233], v[206:209], v[36:39]
	v_mfma_f32_16x16x32_bf16 v[32:35], v[234:237], v[202:205], v[32:35]
	v_mfma_f32_16x16x32_bf16 v[32:35], v[238:241], v[206:209], v[32:35]
	v_mfma_f32_16x16x32_bf16 v[20:23], v[226:229], v[210:213], v[20:23]
	v_mfma_f32_16x16x32_bf16 v[20:23], v[230:233], v[214:217], v[20:23]
	v_mfma_f32_16x16x32_bf16 v[16:19], v[234:237], v[210:213], v[16:19]
	v_mfma_f32_16x16x32_bf16 v[16:19], v[238:241], v[214:217], v[16:19]
	v_mfma_f32_16x16x32_bf16 v[4:7], v[226:229], v[218:221], v[4:7]
	v_mfma_f32_16x16x32_bf16 v[4:7], v[230:233], v[222:225], v[4:7]
	v_mfma_f32_16x16x32_bf16 v[0:3], v[234:237], v[218:221], v[0:3]
	v_mfma_f32_16x16x32_bf16 v[0:3], v[238:241], v[222:225], v[0:3]
	s_add_i32 s54, s54, 2
	s_add_u32 s38, s38, 0x100
	s_addc_u32 s39, s39, 0
	s_add_u32 s27, s27, 0x100
	s_addc_u32 s29, s29, 0
	s_cmp_gt_u32 s54, 61
	s_barrier
	s_cbranch_scc0 .LBB0_127
	v_lshl_or_b32 v156, s8, 8, v166
	s_waitcnt vmcnt(0)
	v_pk_mul_f32 v[126:127], v[160:161], v[126:127] op_sel_hi:[0,1]
	v_pk_mul_f32 v[124:125], v[160:161], v[124:125] op_sel_hi:[0,1]
	v_pk_mul_f32 v[122:123], v[160:161], v[122:123] op_sel_hi:[0,1]
	v_pk_mul_f32 v[162:163], v[160:161], v[120:121] op_sel_hi:[0,1]
	v_cmp_lt_i32_e64 s[8:9], s74, v156
	s_and_saveexec_b64 s[38:39], s[8:9]
	s_cbranch_execz .LBB0_130
	v_mul_f32_e32 v147, 0xbfb8aa3b, v126
	v_mul_f32_e32 v121, 0xbfb8aa3b, v162
	v_exp_f32_e32 v147, v147
	v_mul_f32_e32 v149, 0xbfb8aa3b, v122
	v_mul_f32_e32 v137, 0xbfb8aa3b, v125
	v_exp_f32_e32 v121, v121
	v_exp_f32_e32 v149, v149
	v_exp_f32_e32 v137, v137
	v_add_f32_e32 v147, 1.0, v147
	v_add_f32_e32 v121, 1.0, v121
	v_rcp_f32_e32 v176, v147
	v_add_f32_e32 v147, 1.0, v149
	v_mul_f32_e32 v149, 0xbfb8aa3b, v127
	v_mul_f32_e32 v120, 0xbfb8aa3b, v124
	v_rcp_f32_e32 v170, v121
	v_add_f32_e32 v121, 1.0, v137
	v_mul_f32_e32 v137, 0xbfb8aa3b, v163
	v_exp_f32_e32 v149, v149
	v_mul_f32_e32 v151, 0xbfb8aa3b, v123
	v_exp_f32_e32 v120, v120
	v_exp_f32_e32 v137, v137
	v_exp_f32_e32 v151, v151
	v_rcp_f32_e32 v178, v147
	v_add_f32_e32 v147, 1.0, v149
	v_add_f32_e32 v120, 1.0, v120
	v_add_f32_e32 v137, 1.0, v137
	v_rcp_f32_e32 v177, v147
	v_add_f32_e32 v147, 1.0, v151
	v_rcp_f32_e32 v120, v120
	v_rcp_f32_e32 v121, v121
	v_rcp_f32_e32 v179, v147
	v_rcp_f32_e32 v171, v137
	v_pk_mul_f32 v[126:127], v[126:127], v[176:177]
	v_pk_mul_f32 v[124:125], v[124:125], v[120:121]
	v_pk_mul_f32 v[122:123], v[122:123], v[178:179]
	v_pk_mul_f32 v[162:163], v[162:163], v[170:171]

.LBB0_301:
	ds_read_b128 v[160:163], v151
	ds_read_b128 v[164:167], v151 offset:1024
	ds_read_b128 v[168:171], v151 offset:2048
	ds_read_b128 v[176:179], v151 offset:3072
	s_add_u32 s44, s42, 0x100
	s_addc_u32 s45, s43, 0
	s_cmp_eq_u32 s83, 12
	s_cselect_b32 s49, s39, s45
	s_cselect_b32 s48, s38, s44
	s_cselect_b32 s47, s37, s82
	s_cselect_b32 s46, s62, s63
	v_lshl_add_u64 v[214:215], s[42:43], 0, v[142:143]
	s_add_i32 m0, s50, 0xc000
	ds_read_b128 v[180:183], v153
	ds_read_b128 v[186:189], v153 offset:1024
	ds_read_b128 v[190:193], v153 offset:2048
	ds_read_b128 v[194:197], v153 offset:3072
	ds_read_b128 v[198:201], v153 offset:4096
	ds_read_b128 v[202:205], v153 offset:5120
	ds_read_b128 v[206:209], v153 offset:6144
	ds_read_b128 v[210:213], v153 offset:7168
	global_load_lds_dwordx4 v[214:215], off
	v_lshl_add_u64 v[214:215], s[42:43], 0, v[144:145]
	s_add_i32 m0, s50, 0xe000
	s_nop 0
	global_load_lds_dwordx4 v[214:215], off
	s_waitcnt lgkmcnt(8)
	s_barrier
	s_waitcnt lgkmcnt(0)
	s_waitcnt lgkmcnt(0)
	v_mfma_f32_16x16x32_bf16 v[124:127], v[160:163], v[180:183], v[124:127]
	v_mfma_f32_16x16x32_bf16 v[124:127], v[164:167], v[186:189], v[124:127]
	v_mfma_f32_16x16x32_bf16 v[120:123], v[168:171], v[180:183], v[120:123]
	v_mfma_f32_16x16x32_bf16 v[120:123], v[176:179], v[186:189], v[120:123]
	v_mfma_f32_16x16x32_bf16 v[112:115], v[160:163], v[190:193], v[112:115]
	v_mfma_f32_16x16x32_bf16 v[112:115], v[164:167], v[194:197], v[112:115]
	v_mfma_f32_16x16x32_bf16 v[104:107], v[168:171], v[190:193], v[104:107]
	v_mfma_f32_16x16x32_bf16 v[104:107], v[176:179], v[194:197], v[104:107]
	v_mfma_f32_16x16x32_bf16 v[96:99], v[160:163], v[198:201], v[96:99]
	v_mfma_f32_16x16x32_bf16 v[96:99], v[164:167], v[202:205], v[96:99]
	v_mfma_f32_16x16x32_bf16 v[88:91], v[168:171], v[198:201], v[88:91]
	v_mfma_f32_16x16x32_bf16 v[88:91], v[176:179], v[202:205], v[88:91]
	v_mfma_f32_16x16x32_bf16 v[80:83], v[160:163], v[206:209], v[80:83]
	v_mfma_f32_16x16x32_bf16 v[80:83], v[164:167], v[210:213], v[80:83]
	v_mfma_f32_16x16x32_bf16 v[72:75], v[168:171], v[206:209], v[72:75]
	v_mfma_f32_16x16x32_bf16 v[72:75], v[176:179], v[210:213], v[72:75]
	s_barrier
	s_add_i32 s42, s76, s5
	v_lshl_add_u64 v[230:231], s[46:47], 0, v[132:133]
	s_mov_b32 m0, s42
	ds_read_b128 v[214:217], v155
	ds_read_b128 v[218:221], v155 offset:1024
	ds_read_b128 v[222:225], v155 offset:2048
	ds_read_b128 v[226:229], v155 offset:3072
	global_load_lds_dwordx4 v[230:231], off
	v_lshl_add_u64 v[232:233], s[46:47], 0, v[128:129]
	s_add_i32 m0, s42, 0x2000
	s_nop 0
	global_load_lds_dwordx4 v[232:233], off
	s_barrier
	s_waitcnt lgkmcnt(0)
	s_waitcnt lgkmcnt(0)
	v_mfma_f32_16x16x32_bf16 v[116:119], v[214:217], v[180:183], v[116:119]
	v_mfma_f32_16x16x32_bf16 v[116:119], v[218:221], v[186:189], v[116:119]
	v_mfma_f32_16x16x32_bf16 v[108:111], v[222:225], v[180:183], v[108:111]
	v_mfma_f32_16x16x32_bf16 v[108:111], v[226:229], v[186:189], v[108:111]
	v_mfma_f32_16x16x32_bf16 v[100:103], v[214:217], v[190:193], v[100:103]
	v_mfma_f32_16x16x32_bf16 v[100:103], v[218:221], v[194:197], v[100:103]
	v_mfma_f32_16x16x32_bf16 v[92:95], v[222:225], v[190:193], v[92:95]
	v_mfma_f32_16x16x32_bf16 v[92:95], v[226:229], v[194:197], v[92:95]
	v_mfma_f32_16x16x32_bf16 v[84:87], v[214:217], v[198:201], v[84:87]
	v_mfma_f32_16x16x32_bf16 v[84:87], v[218:221], v[202:205], v[84:87]
	v_mfma_f32_16x16x32_bf16 v[76:79], v[222:225], v[198:201], v[76:79]
	v_mfma_f32_16x16x32_bf16 v[76:79], v[226:229], v[202:205], v[76:79]
	v_mfma_f32_16x16x32_bf16 v[68:71], v[214:217], v[206:209], v[68:71]
	v_mfma_f32_16x16x32_bf16 v[68:71], v[218:221], v[210:213], v[68:71]
	v_mfma_f32_16x16x32_bf16 v[64:67], v[222:225], v[206:209], v[64:67]
	v_mfma_f32_16x16x32_bf16 v[64:67], v[226:229], v[210:213], v[64:67]
	s_mov_b32 m0, s50
	v_lshl_add_u64 v[234:235], s[48:49], 0, v[134:135]
	s_barrier
	ds_read_b128 v[180:183], v153 offset:16384
	ds_read_b128 v[186:189], v153 offset:17408
	ds_read_b128 v[190:193], v153 offset:18432
	ds_read_b128 v[194:197], v153 offset:19456
	ds_read_b128 v[198:201], v153 offset:20480
	ds_read_b128 v[202:205], v153 offset:21504
	ds_read_b128 v[206:209], v153 offset:22528
	ds_read_b128 v[210:213], v153 offset:23552
	global_load_lds_dwordx4 v[234:235], off
	v_lshl_add_u64 v[236:237], s[48:49], 0, v[130:131]
	s_mov_b32 m0, s51
	s_nop 0
	global_load_lds_dwordx4 v[236:237], off
	s_barrier
	s_waitcnt lgkmcnt(0)
	s_waitcnt lgkmcnt(0)
	v_mfma_f32_16x16x32_bf16 v[60:63], v[160:163], v[180:183], v[60:63]
	v_mfma_f32_16x16x32_bf16 v[60:63], v[164:167], v[186:189], v[60:63]
	v_mfma_f32_16x16x32_bf16 v[56:59], v[168:171], v[180:183], v[56:59]
	v_mfma_f32_16x16x32_bf16 v[56:59], v[176:179], v[186:189], v[56:59]
	v_mfma_f32_16x16x32_bf16 v[48:51], v[160:163], v[190:193], v[48:51]
	v_mfma_f32_16x16x32_bf16 v[48:51], v[164:167], v[194:197], v[48:51]
	v_mfma_f32_16x16x32_bf16 v[40:43], v[168:171], v[190:193], v[40:43]
	v_mfma_f32_16x16x32_bf16 v[40:43], v[176:179], v[194:197], v[40:43]
	v_mfma_f32_16x16x32_bf16 v[32:35], v[160:163], v[198:201], v[32:35]
	v_mfma_f32_16x16x32_bf16 v[32:35], v[164:167], v[202:205], v[32:35]
	v_mfma_f32_16x16x32_bf16 v[24:27], v[168:171], v[198:201], v[24:27]
	v_mfma_f32_16x16x32_bf16 v[24:27], v[176:179], v[202:205], v[24:27]
	v_mfma_f32_16x16x32_bf16 v[16:19], v[160:163], v[206:209], v[16:19]
	v_mfma_f32_16x16x32_bf16 v[16:19], v[164:167], v[210:213], v[16:19]
	v_mfma_f32_16x16x32_bf16 v[8:11], v[168:171], v[206:209], v[8:11]
	v_mfma_f32_16x16x32_bf16 v[8:11], v[176:179], v[210:213], v[8:11]
	s_barrier
	s_add_u32 s42, s46, 0x40000
	s_addc_u32 s43, s47, 0
	s_add_i32 s84, s77, s5
	v_lshl_add_u64 v[160:161], s[42:43], 0, v[132:133]
	s_mov_b32 m0, s84
	s_nop 0
	global_load_lds_dwordx4 v[160:161], off
	v_lshl_add_u64 v[160:161], s[42:43], 0, v[128:129]
	s_add_i32 m0, s84, 0x2000
	s_nop 0
	global_load_lds_dwordx4 v[160:161], off
	s_waitcnt vmcnt(6)
	s_barrier
	v_mfma_f32_16x16x32_bf16 v[52:55], v[214:217], v[180:183], v[52:55]
	v_mfma_f32_16x16x32_bf16 v[52:55], v[218:221], v[186:189], v[52:55]
	v_mfma_f32_16x16x32_bf16 v[44:47], v[222:225], v[180:183], v[44:47]
	v_mfma_f32_16x16x32_bf16 v[44:47], v[226:229], v[186:189], v[44:47]
	v_mfma_f32_16x16x32_bf16 v[36:39], v[214:217], v[190:193], v[36:39]
	v_mfma_f32_16x16x32_bf16 v[36:39], v[218:221], v[194:197], v[36:39]
	v_mfma_f32_16x16x32_bf16 v[28:31], v[222:225], v[190:193], v[28:31]
	v_mfma_f32_16x16x32_bf16 v[28:31], v[226:229], v[194:197], v[28:31]
	v_mfma_f32_16x16x32_bf16 v[20:23], v[214:217], v[198:201], v[20:23]
	v_mfma_f32_16x16x32_bf16 v[20:23], v[218:221], v[202:205], v[20:23]
	v_mfma_f32_16x16x32_bf16 v[12:15], v[222:225], v[198:201], v[12:15]
	v_mfma_f32_16x16x32_bf16 v[12:15], v[226:229], v[202:205], v[12:15]
	v_mfma_f32_16x16x32_bf16 v[4:7], v[214:217], v[206:209], v[4:7]
	v_mfma_f32_16x16x32_bf16 v[4:7], v[218:221], v[210:213], v[4:7]
	v_mfma_f32_16x16x32_bf16 v[0:3], v[222:225], v[206:209], v[0:3]
	v_mfma_f32_16x16x32_bf16 v[0:3], v[226:229], v[210:213], v[0:3]
	s_add_i32 s84, 0, 0x18000
	v_add_u32_e32 v157, s84, v139
	s_barrier
	ds_read_b128 v[160:163], v157
	ds_read_b128 v[164:167], v157 offset:1024
	ds_read_b128 v[168:171], v157 offset:2048
	ds_read_b128 v[176:179], v157 offset:3072
	s_add_u32 s42, s48, 0x170000
	s_addc_u32 s43, s49, 0
	s_mov_b32 m0, s52
	v_lshl_add_u64 v[214:215], s[42:43], 0, v[134:135]
	ds_read_b128 v[180:183], v153 offset:32768
	ds_read_b128 v[186:189], v153 offset:33792
	ds_read_b128 v[190:193], v153 offset:34816
	ds_read_b128 v[194:197], v153 offset:35840
	ds_read_b128 v[198:201], v153 offset:36864
	ds_read_b128 v[202:205], v153 offset:37888
	ds_read_b128 v[206:209], v153 offset:38912
	ds_read_b128 v[210:213], v153 offset:39936
	global_load_lds_dwordx4 v[214:215], off
	v_lshl_add_u64 v[214:215], s[42:43], 0, v[130:131]
	s_mov_b32 m0, s53
	s_nop 0
	global_load_lds_dwordx4 v[214:215], off
	s_waitcnt lgkmcnt(8)
	s_barrier
	s_waitcnt lgkmcnt(0)
	s_waitcnt lgkmcnt(0)
	v_mfma_f32_16x16x32_bf16 v[124:127], v[160:163], v[180:183], v[124:127]
	v_mfma_f32_16x16x32_bf16 v[124:127], v[164:167], v[186:189], v[124:127]
	v_mfma_f32_16x16x32_bf16 v[120:123], v[168:171], v[180:183], v[120:123]
	v_mfma_f32_16x16x32_bf16 v[120:123], v[176:179], v[186:189], v[120:123]
	v_mfma_f32_16x16x32_bf16 v[112:115], v[160:163], v[190:193], v[112:115]
	v_mfma_f32_16x16x32_bf16 v[112:115], v[164:167], v[194:197], v[112:115]
	v_mfma_f32_16x16x32_bf16 v[104:107], v[168:171], v[190:193], v[104:107]
	v_mfma_f32_16x16x32_bf16 v[104:107], v[176:179], v[194:197], v[104:107]
	v_mfma_f32_16x16x32_bf16 v[96:99], v[160:163], v[198:201], v[96:99]
	v_mfma_f32_16x16x32_bf16 v[96:99], v[164:167], v[202:205], v[96:99]
	v_mfma_f32_16x16x32_bf16 v[88:91], v[168:171], v[198:201], v[88:91]
	v_mfma_f32_16x16x32_bf16 v[88:91], v[176:179], v[202:205], v[88:91]
	v_mfma_f32_16x16x32_bf16 v[80:83], v[160:163], v[206:209], v[80:83]
	v_mfma_f32_16x16x32_bf16 v[80:83], v[164:167], v[210:213], v[80:83]
	v_mfma_f32_16x16x32_bf16 v[72:75], v[168:171], v[206:209], v[72:75]
	v_mfma_f32_16x16x32_bf16 v[72:75], v[176:179], v[210:213], v[72:75]
	s_barrier
	s_add_i32 s48, 0, 0x1c000
	s_add_i32 s42, s84, s5
	v_add_u32_e32 v157, s48, v139
	v_lshl_add_u64 v[230:231], v[230:231], 0, s[10:11]
	s_mov_b32 m0, s42
	ds_read_b128 v[214:217], v157
	ds_read_b128 v[218:221], v157 offset:1024
	ds_read_b128 v[222:225], v157 offset:2048
	ds_read_b128 v[226:229], v157 offset:3072
	global_load_lds_dwordx4 v[230:231], off
	v_lshl_add_u64 v[230:231], v[232:233], 0, s[10:11]
	s_add_i32 m0, s42, 0x2000
	s_nop 0
	global_load_lds_dwordx4 v[230:231], off
	s_barrier
	s_waitcnt lgkmcnt(0)
	s_waitcnt lgkmcnt(0)
	v_mfma_f32_16x16x32_bf16 v[116:119], v[214:217], v[180:183], v[116:119]
	v_mfma_f32_16x16x32_bf16 v[116:119], v[218:221], v[186:189], v[116:119]
	v_mfma_f32_16x16x32_bf16 v[108:111], v[222:225], v[180:183], v[108:111]
	v_mfma_f32_16x16x32_bf16 v[108:111], v[226:229], v[186:189], v[108:111]
	v_mfma_f32_16x16x32_bf16 v[100:103], v[214:217], v[190:193], v[100:103]
	v_mfma_f32_16x16x32_bf16 v[100:103], v[218:221], v[194:197], v[100:103]
	v_mfma_f32_16x16x32_bf16 v[92:95], v[222:225], v[190:193], v[92:95]
	v_mfma_f32_16x16x32_bf16 v[92:95], v[226:229], v[194:197], v[92:95]
	v_mfma_f32_16x16x32_bf16 v[84:87], v[214:217], v[198:201], v[84:87]
	v_mfma_f32_16x16x32_bf16 v[84:87], v[218:221], v[202:205], v[84:87]
	v_mfma_f32_16x16x32_bf16 v[76:79], v[222:225], v[198:201], v[76:79]
	v_mfma_f32_16x16x32_bf16 v[76:79], v[226:229], v[202:205], v[76:79]
	v_mfma_f32_16x16x32_bf16 v[68:71], v[214:217], v[206:209], v[68:71]
	v_mfma_f32_16x16x32_bf16 v[68:71], v[218:221], v[210:213], v[68:71]
	v_mfma_f32_16x16x32_bf16 v[64:67], v[222:225], v[206:209], v[64:67]
	v_mfma_f32_16x16x32_bf16 v[64:67], v[226:229], v[210:213], v[64:67]
	s_mov_b32 m0, s55
	v_lshl_add_u64 v[230:231], v[234:235], 0, s[10:11]
	s_barrier
	ds_read_b128 v[180:183], v153 offset:49152
	ds_read_b128 v[186:189], v153 offset:50176
	ds_read_b128 v[190:193], v153 offset:51200
	ds_read_b128 v[194:197], v153 offset:52224
	ds_read_b128 v[198:201], v153 offset:53248
	ds_read_b128 v[202:205], v153 offset:54272
	ds_read_b128 v[206:209], v153 offset:55296
	ds_read_b128 v[210:213], v153 offset:56320
	global_load_lds_dwordx4 v[230:231], off
	v_lshl_add_u64 v[230:231], v[236:237], 0, s[10:11]
	s_mov_b32 m0, s61
	s_nop 0
	global_load_lds_dwordx4 v[230:231], off
	s_barrier
	s_waitcnt lgkmcnt(0)
	s_waitcnt lgkmcnt(0)
	v_mfma_f32_16x16x32_bf16 v[60:63], v[160:163], v[180:183], v[60:63]
	v_mfma_f32_16x16x32_bf16 v[60:63], v[164:167], v[186:189], v[60:63]
	v_mfma_f32_16x16x32_bf16 v[56:59], v[168:171], v[180:183], v[56:59]
	v_mfma_f32_16x16x32_bf16 v[56:59], v[176:179], v[186:189], v[56:59]
	v_mfma_f32_16x16x32_bf16 v[48:51], v[160:163], v[190:193], v[48:51]
	v_mfma_f32_16x16x32_bf16 v[48:51], v[164:167], v[194:197], v[48:51]
	v_mfma_f32_16x16x32_bf16 v[40:43], v[168:171], v[190:193], v[40:43]
	v_mfma_f32_16x16x32_bf16 v[40:43], v[176:179], v[194:197], v[40:43]
	v_mfma_f32_16x16x32_bf16 v[32:35], v[160:163], v[198:201], v[32:35]
	v_mfma_f32_16x16x32_bf16 v[32:35], v[164:167], v[202:205], v[32:35]
	v_mfma_f32_16x16x32_bf16 v[24:27], v[168:171], v[198:201], v[24:27]
	v_mfma_f32_16x16x32_bf16 v[24:27], v[176:179], v[202:205], v[24:27]
	v_mfma_f32_16x16x32_bf16 v[16:19], v[160:163], v[206:209], v[16:19]
	v_mfma_f32_16x16x32_bf16 v[16:19], v[164:167], v[210:213], v[16:19]
	v_mfma_f32_16x16x32_bf16 v[8:11], v[168:171], v[206:209], v[8:11]
	v_mfma_f32_16x16x32_bf16 v[8:11], v[176:179], v[210:213], v[8:11]
	s_barrier
	s_add_u32 s42, s46, 0x40080
	s_addc_u32 s43, s47, 0
	s_add_i32 s46, s48, s5
	v_lshl_add_u64 v[160:161], s[42:43], 0, v[132:133]
	s_mov_b32 m0, s46
	s_nop 0
	global_load_lds_dwordx4 v[160:161], off
	v_lshl_add_u64 v[160:161], s[42:43], 0, v[128:129]
	s_add_i32 m0, s46, 0x2000
	s_nop 0
	global_load_lds_dwordx4 v[160:161], off
	s_waitcnt vmcnt(6)
	s_barrier
	v_mfma_f32_16x16x32_bf16 v[52:55], v[214:217], v[180:183], v[52:55]
	v_mfma_f32_16x16x32_bf16 v[52:55], v[218:221], v[186:189], v[52:55]
	v_mfma_f32_16x16x32_bf16 v[44:47], v[222:225], v[180:183], v[44:47]
	v_mfma_f32_16x16x32_bf16 v[44:47], v[226:229], v[186:189], v[44:47]
	v_mfma_f32_16x16x32_bf16 v[36:39], v[214:217], v[190:193], v[36:39]
	v_mfma_f32_16x16x32_bf16 v[36:39], v[218:221], v[194:197], v[36:39]
	v_mfma_f32_16x16x32_bf16 v[28:31], v[222:225], v[190:193], v[28:31]
	v_mfma_f32_16x16x32_bf16 v[28:31], v[226:229], v[194:197], v[28:31]
	v_mfma_f32_16x16x32_bf16 v[20:23], v[214:217], v[198:201], v[20:23]
	v_mfma_f32_16x16x32_bf16 v[20:23], v[218:221], v[202:205], v[20:23]
	v_mfma_f32_16x16x32_bf16 v[12:15], v[222:225], v[198:201], v[12:15]
	v_mfma_f32_16x16x32_bf16 v[12:15], v[226:229], v[202:205], v[12:15]
	v_mfma_f32_16x16x32_bf16 v[4:7], v[214:217], v[206:209], v[4:7]
	v_mfma_f32_16x16x32_bf16 v[4:7], v[218:221], v[210:213], v[4:7]
	v_mfma_f32_16x16x32_bf16 v[0:3], v[222:225], v[206:209], v[0:3]
	v_mfma_f32_16x16x32_bf16 v[0:3], v[226:229], v[210:213], v[0:3]
	s_add_i32 s83, s83, 2
	s_add_u32 s63, s63, 0x100
	s_addc_u32 s82, s82, 0
	s_cmp_gt_u32 s83, 13
	s_mov_b64 s[42:43], s[44:45]
	s_barrier
	s_cbranch_scc0 .LBB0_301
	v_lshl_or_b32 v162, s81, 8, v141
	v_lshl_add_u32 v157, s80, 8, v137
	v_ashrrev_i32_e32 v163, 31, v162
	v_mov_b64_e32 v[160:161], s[12:13]
	v_mad_i64_i32 v[164:165], s[42:43], v157, s78, v[160:161]
	v_lshlrev_b64 v[162:163], 1, v[162:163]
	v_lshl_add_u64 v[164:165], v[164:165], 0, v[162:163]
	s_waitcnt vmcnt(0)
	v_pk_mul_f32 v[126:127], v[158:159], v[126:127] op_sel_hi:[0,1]
	v_pk_mul_f32 v[124:125], v[158:159], v[124:125] op_sel_hi:[0,1]
	v_pk_mul_f32 v[166:167], v[158:159], v[122:123] op_sel_hi:[0,1]
	v_pk_mul_f32 v[122:123], v[158:159], v[120:121] op_sel_hi:[0,1]
	v_cvt_pk_bf16_f32 v120, v124, v125
	v_cvt_pk_bf16_f32 v121, v126, v127
	v_cvt_pk_bf16_f32 v122, v122, v123
	v_cvt_pk_bf16_f32 v123, v166, v167
	global_store_dwordx4 v[164:165], v[120:123], off
	v_pk_mul_f32 v[116:117], v[158:159], v[116:117] op_sel_hi:[0,1]
	v_pk_mul_f32 v[118:119], v[158:159], v[118:119] op_sel_hi:[0,1]
	v_pk_mul_f32 v[120:121], v[158:159], v[110:111] op_sel_hi:[0,1]
	v_pk_mul_f32 v[110:111], v[158:159], v[108:109] op_sel_hi:[0,1]
	v_cvt_pk_bf16_f32 v108, v116, v117
	v_cvt_pk_bf16_f32 v109, v118, v119
	v_cvt_pk_bf16_f32 v110, v110, v111
	v_cvt_pk_bf16_f32 v111, v120, v121
	global_store_dwordx4 v[164:165], v[108:111], off offset:256
	v_pk_mul_f32 v[112:113], v[156:157], v[112:113] op_sel_hi:[0,1]
	v_pk_mul_f32 v[100:101], v[156:157], v[100:101] op_sel_hi:[0,1]
	v_or_b32_e32 v108, 16, v157
	v_mad_i64_i32 v[108:109], s[42:43], v108, s78, v[160:161]
	v_lshl_add_u64 v[108:109], v[108:109], 0, v[162:163]
	v_pk_mul_f32 v[110:111], v[156:157], v[114:115] op_sel_hi:[0,1]
	v_pk_mul_f32 v[114:115], v[156:157], v[106:107] op_sel_hi:[0,1]
	v_pk_mul_f32 v[106:107], v[156:157], v[104:105] op_sel_hi:[0,1]
	v_cvt_pk_bf16_f32 v104, v112, v113
	v_cvt_pk_bf16_f32 v105, v110, v111
	v_cvt_pk_bf16_f32 v106, v106, v107
	v_cvt_pk_bf16_f32 v107, v114, v115
	global_store_dwordx4 v[108:109], v[104:107], off
	v_pk_mul_f32 v[102:103], v[156:157], v[102:103] op_sel_hi:[0,1]
	v_pk_mul_f32 v[96:97], v[154:155], v[96:97] op_sel_hi:[0,1]
	v_pk_mul_f32 v[104:105], v[156:157], v[94:95] op_sel_hi:[0,1]
	v_pk_mul_f32 v[94:95], v[156:157], v[92:93] op_sel_hi:[0,1]
	v_cvt_pk_bf16_f32 v92, v100, v101
	v_cvt_pk_bf16_f32 v93, v102, v103
	v_cvt_pk_bf16_f32 v94, v94, v95
	v_cvt_pk_bf16_f32 v95, v104, v105
	global_store_dwordx4 v[108:109], v[92:95], off offset:256
	v_pk_mul_f32 v[84:85], v[154:155], v[84:85] op_sel_hi:[0,1]
	v_pk_mul_f32 v[86:87], v[154:155], v[86:87] op_sel_hi:[0,1]
	v_or_b32_e32 v92, 32, v157
	v_mad_i64_i32 v[92:93], s[42:43], v92, s78, v[160:161]
	v_lshl_add_u64 v[92:93], v[92:93], 0, v[162:163]
	v_pk_mul_f32 v[94:95], v[154:155], v[98:99] op_sel_hi:[0,1]
	v_pk_mul_f32 v[98:99], v[154:155], v[90:91] op_sel_hi:[0,1]
	v_pk_mul_f32 v[90:91], v[154:155], v[88:89] op_sel_hi:[0,1]
	v_cvt_pk_bf16_f32 v88, v96, v97
	v_cvt_pk_bf16_f32 v89, v94, v95
	v_cvt_pk_bf16_f32 v90, v90, v91
	v_cvt_pk_bf16_f32 v91, v98, v99
	global_store_dwordx4 v[92:93], v[88:91], off
	v_pk_mul_f32 v[80:81], v[152:153], v[80:81] op_sel_hi:[0,1]
	v_pk_mul_f32 v[68:69], v[152:153], v[68:69] op_sel_hi:[0,1]
	v_pk_mul_f32 v[88:89], v[154:155], v[78:79] op_sel_hi:[0,1]
	v_pk_mul_f32 v[78:79], v[154:155], v[76:77] op_sel_hi:[0,1]
	v_cvt_pk_bf16_f32 v76, v84, v85
	v_cvt_pk_bf16_f32 v77, v86, v87
	v_cvt_pk_bf16_f32 v78, v78, v79
	v_cvt_pk_bf16_f32 v79, v88, v89
	global_store_dwordx4 v[92:93], v[76:79], off offset:256
	v_pk_mul_f32 v[70:71], v[152:153], v[70:71] op_sel_hi:[0,1]
	v_pk_mul_f32 v[62:63], v[150:151], v[62:63] op_sel_hi:[0,1]
	v_or_b32_e32 v76, 48, v157
	v_mad_i64_i32 v[76:77], s[42:43], v76, s78, v[160:161]
	v_lshl_add_u64 v[76:77], v[76:77], 0, v[162:163]
	v_pk_mul_f32 v[78:79], v[152:153], v[82:83] op_sel_hi:[0,1]
	v_pk_mul_f32 v[82:83], v[152:153], v[74:75] op_sel_hi:[0,1]
	v_pk_mul_f32 v[74:75], v[152:153], v[72:73] op_sel_hi:[0,1]
	v_cvt_pk_bf16_f32 v72, v80, v81
	v_cvt_pk_bf16_f32 v73, v78, v79
	v_cvt_pk_bf16_f32 v74, v74, v75
	v_cvt_pk_bf16_f32 v75, v82, v83
	global_store_dwordx4 v[76:77], v[72:75], off
	v_pk_mul_f32 v[60:61], v[150:151], v[60:61] op_sel_hi:[0,1]
	v_pk_mul_f32 v[52:53], v[150:151], v[52:53] op_sel_hi:[0,1]
	v_pk_mul_f32 v[72:73], v[152:153], v[66:67] op_sel_hi:[0,1]
	v_pk_mul_f32 v[66:67], v[152:153], v[64:65] op_sel_hi:[0,1]
	v_cvt_pk_bf16_f32 v64, v68, v69
	v_cvt_pk_bf16_f32 v65, v70, v71
	v_cvt_pk_bf16_f32 v66, v66, v67
	v_cvt_pk_bf16_f32 v67, v72, v73
	global_store_dwordx4 v[76:77], v[64:67], off offset:256
	v_pk_mul_f32 v[54:55], v[150:151], v[54:55] op_sel_hi:[0,1]
	v_pk_mul_f32 v[48:49], v[140:141], v[48:49] op_sel_hi:[0,1]
	v_add_u32_e32 v64, 0x80, v157
	v_mad_i64_i32 v[64:65], s[42:43], v64, s78, v[160:161]
	v_lshl_add_u64 v[64:65], v[64:65], 0, v[162:163]
	v_pk_mul_f32 v[66:67], v[150:151], v[58:59] op_sel_hi:[0,1]
	v_pk_mul_f32 v[58:59], v[150:151], v[56:57] op_sel_hi:[0,1]
	v_cvt_pk_bf16_f32 v56, v60, v61
	v_cvt_pk_bf16_f32 v57, v62, v63
	v_cvt_pk_bf16_f32 v58, v58, v59
	v_cvt_pk_bf16_f32 v59, v66, v67
	global_store_dwordx4 v[64:65], v[56:59], off
	v_pk_mul_f32 v[36:37], v[140:141], v[36:37] op_sel_hi:[0,1]
	v_pk_mul_f32 v[38:39], v[140:141], v[38:39] op_sel_hi:[0,1]
	v_pk_mul_f32 v[56:57], v[150:151], v[46:47] op_sel_hi:[0,1]
	v_pk_mul_f32 v[46:47], v[150:151], v[44:45] op_sel_hi:[0,1]
	v_cvt_pk_bf16_f32 v44, v52, v53
	v_cvt_pk_bf16_f32 v45, v54, v55
	v_cvt_pk_bf16_f32 v46, v46, v47
	v_cvt_pk_bf16_f32 v47, v56, v57
	global_store_dwordx4 v[64:65], v[44:47], off offset:256
	v_pk_mul_f32 v[32:33], v[138:139], v[32:33] op_sel_hi:[0,1]
	v_pk_mul_f32 v[20:21], v[138:139], v[20:21] op_sel_hi:[0,1]
	v_add_u32_e32 v44, 0x90, v157
	v_mad_i64_i32 v[44:45], s[42:43], v44, s78, v[160:161]
	v_lshl_add_u64 v[44:45], v[44:45], 0, v[162:163]
	v_pk_mul_f32 v[46:47], v[140:141], v[50:51] op_sel_hi:[0,1]
	v_pk_mul_f32 v[50:51], v[140:141], v[42:43] op_sel_hi:[0,1]
	v_pk_mul_f32 v[42:43], v[140:141], v[40:41] op_sel_hi:[0,1]
	v_cvt_pk_bf16_f32 v40, v48, v49
	v_cvt_pk_bf16_f32 v41, v46, v47
	v_cvt_pk_bf16_f32 v42, v42, v43
	v_cvt_pk_bf16_f32 v43, v50, v51
	global_store_dwordx4 v[44:45], v[40:43], off
	v_pk_mul_f32 v[22:23], v[138:139], v[22:23] op_sel_hi:[0,1]
	v_pk_mul_f32 v[16:17], v[136:137], v[16:17] op_sel_hi:[0,1]
	v_pk_mul_f32 v[40:41], v[140:141], v[30:31] op_sel_hi:[0,1]
	v_pk_mul_f32 v[30:31], v[140:141], v[28:29] op_sel_hi:[0,1]
	v_cvt_pk_bf16_f32 v28, v36, v37
	v_cvt_pk_bf16_f32 v29, v38, v39
	v_cvt_pk_bf16_f32 v30, v30, v31
	v_cvt_pk_bf16_f32 v31, v40, v41
	global_store_dwordx4 v[44:45], v[28:31], off offset:256
	s_and_b64 vcc, s[8:9], exec
	v_pk_mul_f32 v[6:7], v[136:137], v[6:7] op_sel_hi:[0,1]
	v_add_u32_e32 v28, 0xa0, v157
	v_mad_i64_i32 v[28:29], s[42:43], v28, s78, v[160:161]
	v_lshl_add_u64 v[28:29], v[28:29], 0, v[162:163]
	v_pk_mul_f32 v[30:31], v[138:139], v[34:35] op_sel_hi:[0,1]
	v_pk_mul_f32 v[34:35], v[138:139], v[26:27] op_sel_hi:[0,1]
	v_pk_mul_f32 v[26:27], v[138:139], v[24:25] op_sel_hi:[0,1]
	v_cvt_pk_bf16_f32 v24, v32, v33
	v_cvt_pk_bf16_f32 v25, v30, v31
	v_cvt_pk_bf16_f32 v26, v26, v27
	v_cvt_pk_bf16_f32 v27, v34, v35
	global_store_dwordx4 v[28:29], v[24:27], off
	v_pk_mul_f32 v[4:5], v[136:137], v[4:5] op_sel_hi:[0,1]
	s_nop 0
	v_pk_mul_f32 v[24:25], v[138:139], v[14:15] op_sel_hi:[0,1]
	v_pk_mul_f32 v[14:15], v[138:139], v[12:13] op_sel_hi:[0,1]
	v_cvt_pk_bf16_f32 v12, v20, v21
	v_cvt_pk_bf16_f32 v13, v22, v23
	v_cvt_pk_bf16_f32 v14, v14, v15
	v_cvt_pk_bf16_f32 v15, v24, v25
	global_store_dwordx4 v[28:29], v[12:15], off offset:256
	s_nop 1
	v_add_u32_e32 v12, 0xb0, v157
	v_mad_i64_i32 v[12:13], s[42:43], v12, s78, v[160:161]
	v_lshl_add_u64 v[12:13], v[12:13], 0, v[162:163]
	v_pk_mul_f32 v[14:15], v[136:137], v[18:19] op_sel_hi:[0,1]
	v_pk_mul_f32 v[18:19], v[136:137], v[10:11] op_sel_hi:[0,1]
	v_pk_mul_f32 v[10:11], v[136:137], v[8:9] op_sel_hi:[0,1]
	v_cvt_pk_bf16_f32 v8, v16, v17
	v_cvt_pk_bf16_f32 v9, v14, v15
	v_cvt_pk_bf16_f32 v10, v10, v11
	v_cvt_pk_bf16_f32 v11, v18, v19
	global_store_dwordx4 v[12:13], v[8:11], off
	s_mov_b64 s[42:43], -1
	s_nop 0
	v_pk_mul_f32 v[8:9], v[136:137], v[2:3] op_sel_hi:[0,1]
	v_pk_mul_f32 v[2:3], v[136:137], v[0:1] op_sel_hi:[0,1]
	v_cvt_pk_bf16_f32 v0, v4, v5
	v_cvt_pk_bf16_f32 v1, v6, v7
	v_cvt_pk_bf16_f32 v2, v2, v3
	v_cvt_pk_bf16_f32 v3, v8, v9
	global_store_dwordx4 v[12:13], v[0:3], off offset:256
	s_cbranch_vccz .LBB0_295
	s_nop 0
	v_lshl_add_u32 v0, s79, 8, v137
	v_ashrrev_i32_e32 v1, 31, v0
	v_lshl_add_u64 v[0:1], v[0:1], 2, s[72:73]
	global_load_dword v158, v[0:1], off
	global_load_dword v156, v[0:1], off offset:64
	global_load_dword v154, v[0:1], off offset:128
	global_load_dword v152, v[0:1], off offset:192
	global_load_dword v150, v[0:1], off offset:512
	global_load_dword v140, v[0:1], off offset:576
	global_load_dword v138, v[0:1], off offset:640
	global_load_dword v136, v[0:1], off offset:704
	s_mov_b64 s[42:43], 0
	s_branch .LBB0_295

.LBB0_325:
	ds_read_b128 v[160:163], v151
	ds_read_b128 v[164:167], v151 offset:1024
	ds_read_b128 v[168:171], v151 offset:2048
	ds_read_b128 v[176:179], v151 offset:3072
	s_add_u32 s48, s46, 0x100
	s_addc_u32 s49, s47, 0
	s_cmp_eq_u32 s91, 4
	s_cselect_b32 s53, s43, s49
	s_cselect_b32 s52, s42, s48
	s_cselect_b32 s51, s41, s90
	s_cselect_b32 s50, s62, s63
	v_lshl_add_u64 v[214:215], s[46:47], 0, v[142:143]
	s_add_i32 m0, s55, 0xc000
	ds_read_b128 v[180:183], v153
	ds_read_b128 v[186:189], v153 offset:1024
	ds_read_b128 v[190:193], v153 offset:2048
	ds_read_b128 v[194:197], v153 offset:3072
	ds_read_b128 v[198:201], v153 offset:4096
	ds_read_b128 v[202:205], v153 offset:5120
	ds_read_b128 v[206:209], v153 offset:6144
	ds_read_b128 v[210:213], v153 offset:7168
	global_load_lds_dwordx4 v[214:215], off
	v_lshl_add_u64 v[214:215], s[46:47], 0, v[144:145]
	s_add_i32 m0, s55, 0xe000
	s_nop 0
	global_load_lds_dwordx4 v[214:215], off
	s_waitcnt lgkmcnt(8)
	s_barrier
	s_waitcnt lgkmcnt(0)
	s_waitcnt lgkmcnt(0)
	v_mfma_f32_16x16x32_bf16 v[124:127], v[160:163], v[180:183], v[124:127]
	v_mfma_f32_16x16x32_bf16 v[124:127], v[164:167], v[186:189], v[124:127]
	v_mfma_f32_16x16x32_bf16 v[120:123], v[168:171], v[180:183], v[120:123]
	v_mfma_f32_16x16x32_bf16 v[120:123], v[176:179], v[186:189], v[120:123]
	v_mfma_f32_16x16x32_bf16 v[108:111], v[160:163], v[190:193], v[108:111]
	v_mfma_f32_16x16x32_bf16 v[108:111], v[164:167], v[194:197], v[108:111]
	v_mfma_f32_16x16x32_bf16 v[104:107], v[168:171], v[190:193], v[104:107]
	v_mfma_f32_16x16x32_bf16 v[104:107], v[176:179], v[194:197], v[104:107]
	v_mfma_f32_16x16x32_bf16 v[92:95], v[160:163], v[198:201], v[92:95]
	v_mfma_f32_16x16x32_bf16 v[92:95], v[164:167], v[202:205], v[92:95]
	v_mfma_f32_16x16x32_bf16 v[88:91], v[168:171], v[198:201], v[88:91]
	v_mfma_f32_16x16x32_bf16 v[88:91], v[176:179], v[202:205], v[88:91]
	v_mfma_f32_16x16x32_bf16 v[76:79], v[160:163], v[206:209], v[76:79]
	v_mfma_f32_16x16x32_bf16 v[76:79], v[164:167], v[210:213], v[76:79]
	v_mfma_f32_16x16x32_bf16 v[72:75], v[168:171], v[206:209], v[72:75]
	v_mfma_f32_16x16x32_bf16 v[72:75], v[176:179], v[210:213], v[72:75]
	s_barrier
	s_add_i32 s46, s81, s54
	v_lshl_add_u64 v[230:231], s[50:51], 0, v[130:131]
	s_mov_b32 m0, s46
	ds_read_b128 v[214:217], v155
	ds_read_b128 v[218:221], v155 offset:1024
	ds_read_b128 v[222:225], v155 offset:2048
	ds_read_b128 v[226:229], v155 offset:3072
	global_load_lds_dwordx4 v[230:231], off
	v_lshl_add_u64 v[232:233], s[50:51], 0, v[134:135]
	s_add_i32 m0, s46, 0x2000
	s_nop 0
	global_load_lds_dwordx4 v[232:233], off
	s_barrier
	s_waitcnt lgkmcnt(0)
	s_waitcnt lgkmcnt(0)
	v_mfma_f32_16x16x32_bf16 v[116:119], v[214:217], v[180:183], v[116:119]
	v_mfma_f32_16x16x32_bf16 v[116:119], v[218:221], v[186:189], v[116:119]
	v_mfma_f32_16x16x32_bf16 v[112:115], v[222:225], v[180:183], v[112:115]
	v_mfma_f32_16x16x32_bf16 v[112:115], v[226:229], v[186:189], v[112:115]
	v_mfma_f32_16x16x32_bf16 v[100:103], v[214:217], v[190:193], v[100:103]
	v_mfma_f32_16x16x32_bf16 v[100:103], v[218:221], v[194:197], v[100:103]
	v_mfma_f32_16x16x32_bf16 v[96:99], v[222:225], v[190:193], v[96:99]
	v_mfma_f32_16x16x32_bf16 v[96:99], v[226:229], v[194:197], v[96:99]
	v_mfma_f32_16x16x32_bf16 v[84:87], v[214:217], v[198:201], v[84:87]
	v_mfma_f32_16x16x32_bf16 v[84:87], v[218:221], v[202:205], v[84:87]
	v_mfma_f32_16x16x32_bf16 v[80:83], v[222:225], v[198:201], v[80:83]
	v_mfma_f32_16x16x32_bf16 v[80:83], v[226:229], v[202:205], v[80:83]
	v_mfma_f32_16x16x32_bf16 v[68:71], v[214:217], v[206:209], v[68:71]
	v_mfma_f32_16x16x32_bf16 v[68:71], v[218:221], v[210:213], v[68:71]
	v_mfma_f32_16x16x32_bf16 v[64:67], v[222:225], v[206:209], v[64:67]
	v_mfma_f32_16x16x32_bf16 v[64:67], v[226:229], v[210:213], v[64:67]
	s_mov_b32 m0, s55
	v_lshl_add_u64 v[234:235], s[52:53], 0, v[128:129]
	s_barrier
	ds_read_b128 v[180:183], v153 offset:16384
	ds_read_b128 v[186:189], v153 offset:17408
	ds_read_b128 v[190:193], v153 offset:18432
	ds_read_b128 v[194:197], v153 offset:19456
	ds_read_b128 v[198:201], v153 offset:20480
	ds_read_b128 v[202:205], v153 offset:21504
	ds_read_b128 v[206:209], v153 offset:22528
	ds_read_b128 v[210:213], v153 offset:23552
	global_load_lds_dwordx4 v[234:235], off
	v_lshl_add_u64 v[236:237], s[52:53], 0, v[132:133]
	s_mov_b32 m0, s61
	s_nop 0
	global_load_lds_dwordx4 v[236:237], off
	s_barrier
	s_waitcnt lgkmcnt(0)
	s_waitcnt lgkmcnt(0)
	v_mfma_f32_16x16x32_bf16 v[60:63], v[160:163], v[180:183], v[60:63]
	v_mfma_f32_16x16x32_bf16 v[60:63], v[164:167], v[186:189], v[60:63]
	v_mfma_f32_16x16x32_bf16 v[56:59], v[168:171], v[180:183], v[56:59]
	v_mfma_f32_16x16x32_bf16 v[56:59], v[176:179], v[186:189], v[56:59]
	v_mfma_f32_16x16x32_bf16 v[48:51], v[160:163], v[190:193], v[48:51]
	v_mfma_f32_16x16x32_bf16 v[48:51], v[164:167], v[194:197], v[48:51]
	v_mfma_f32_16x16x32_bf16 v[40:43], v[168:171], v[190:193], v[40:43]
	v_mfma_f32_16x16x32_bf16 v[40:43], v[176:179], v[194:197], v[40:43]
	v_mfma_f32_16x16x32_bf16 v[32:35], v[160:163], v[198:201], v[32:35]
	v_mfma_f32_16x16x32_bf16 v[32:35], v[164:167], v[202:205], v[32:35]
	v_mfma_f32_16x16x32_bf16 v[24:27], v[168:171], v[198:201], v[24:27]
	v_mfma_f32_16x16x32_bf16 v[24:27], v[176:179], v[202:205], v[24:27]
	v_mfma_f32_16x16x32_bf16 v[16:19], v[160:163], v[206:209], v[16:19]
	v_mfma_f32_16x16x32_bf16 v[16:19], v[164:167], v[210:213], v[16:19]
	v_mfma_f32_16x16x32_bf16 v[8:11], v[168:171], v[206:209], v[8:11]
	v_mfma_f32_16x16x32_bf16 v[8:11], v[176:179], v[210:213], v[8:11]
	s_barrier
	s_add_u32 s46, s50, 0x20000
	s_addc_u32 s47, s51, 0
	s_add_i32 s92, s82, s54
	v_lshl_add_u64 v[160:161], s[46:47], 0, v[130:131]
	s_mov_b32 m0, s92
	s_nop 0
	global_load_lds_dwordx4 v[160:161], off
	v_lshl_add_u64 v[160:161], s[46:47], 0, v[134:135]
	s_add_i32 m0, s92, 0x2000
	s_nop 0
	global_load_lds_dwordx4 v[160:161], off
	s_waitcnt vmcnt(6)
	s_barrier
	v_mfma_f32_16x16x32_bf16 v[52:55], v[214:217], v[180:183], v[52:55]
	v_mfma_f32_16x16x32_bf16 v[52:55], v[218:221], v[186:189], v[52:55]
	v_mfma_f32_16x16x32_bf16 v[44:47], v[222:225], v[180:183], v[44:47]
	v_mfma_f32_16x16x32_bf16 v[44:47], v[226:229], v[186:189], v[44:47]
	v_mfma_f32_16x16x32_bf16 v[36:39], v[214:217], v[190:193], v[36:39]
	v_mfma_f32_16x16x32_bf16 v[36:39], v[218:221], v[194:197], v[36:39]
	v_mfma_f32_16x16x32_bf16 v[28:31], v[222:225], v[190:193], v[28:31]
	v_mfma_f32_16x16x32_bf16 v[28:31], v[226:229], v[194:197], v[28:31]
	v_mfma_f32_16x16x32_bf16 v[20:23], v[214:217], v[198:201], v[20:23]
	v_mfma_f32_16x16x32_bf16 v[20:23], v[218:221], v[202:205], v[20:23]
	v_mfma_f32_16x16x32_bf16 v[12:15], v[222:225], v[198:201], v[12:15]
	v_mfma_f32_16x16x32_bf16 v[12:15], v[226:229], v[202:205], v[12:15]
	v_mfma_f32_16x16x32_bf16 v[4:7], v[214:217], v[206:209], v[4:7]
	v_mfma_f32_16x16x32_bf16 v[4:7], v[218:221], v[210:213], v[4:7]
	v_mfma_f32_16x16x32_bf16 v[0:3], v[222:225], v[206:209], v[0:3]
	v_mfma_f32_16x16x32_bf16 v[0:3], v[226:229], v[210:213], v[0:3]
	s_add_i32 s92, 0, 0x18000
	v_add_u32_e32 v157, s92, v139
	s_barrier
	ds_read_b128 v[160:163], v157
	ds_read_b128 v[164:167], v157 offset:1024
	ds_read_b128 v[168:171], v157 offset:2048
	ds_read_b128 v[176:179], v157 offset:3072
	s_add_u32 s46, s52, 0x170000
	s_addc_u32 s47, s53, 0
	s_mov_b32 m0, s74
	v_lshl_add_u64 v[214:215], s[46:47], 0, v[128:129]
	ds_read_b128 v[180:183], v153 offset:32768
	ds_read_b128 v[186:189], v153 offset:33792
	ds_read_b128 v[190:193], v153 offset:34816
	ds_read_b128 v[194:197], v153 offset:35840
	ds_read_b128 v[198:201], v153 offset:36864
	ds_read_b128 v[202:205], v153 offset:37888
	ds_read_b128 v[206:209], v153 offset:38912
	ds_read_b128 v[210:213], v153 offset:39936
	global_load_lds_dwordx4 v[214:215], off
	v_lshl_add_u64 v[214:215], s[46:47], 0, v[132:133]
	s_mov_b32 m0, s75
	s_nop 0
	global_load_lds_dwordx4 v[214:215], off
	s_waitcnt lgkmcnt(8)
	s_barrier
	s_waitcnt lgkmcnt(0)
	s_waitcnt lgkmcnt(0)
	v_mfma_f32_16x16x32_bf16 v[124:127], v[160:163], v[180:183], v[124:127]
	v_mfma_f32_16x16x32_bf16 v[124:127], v[164:167], v[186:189], v[124:127]
	v_mfma_f32_16x16x32_bf16 v[120:123], v[168:171], v[180:183], v[120:123]
	v_mfma_f32_16x16x32_bf16 v[120:123], v[176:179], v[186:189], v[120:123]
	v_mfma_f32_16x16x32_bf16 v[108:111], v[160:163], v[190:193], v[108:111]
	v_mfma_f32_16x16x32_bf16 v[108:111], v[164:167], v[194:197], v[108:111]
	v_mfma_f32_16x16x32_bf16 v[104:107], v[168:171], v[190:193], v[104:107]
	v_mfma_f32_16x16x32_bf16 v[104:107], v[176:179], v[194:197], v[104:107]
	v_mfma_f32_16x16x32_bf16 v[92:95], v[160:163], v[198:201], v[92:95]
	v_mfma_f32_16x16x32_bf16 v[92:95], v[164:167], v[202:205], v[92:95]
	v_mfma_f32_16x16x32_bf16 v[88:91], v[168:171], v[198:201], v[88:91]
	v_mfma_f32_16x16x32_bf16 v[88:91], v[176:179], v[202:205], v[88:91]
	v_mfma_f32_16x16x32_bf16 v[76:79], v[160:163], v[206:209], v[76:79]
	v_mfma_f32_16x16x32_bf16 v[76:79], v[164:167], v[210:213], v[76:79]
	v_mfma_f32_16x16x32_bf16 v[72:75], v[168:171], v[206:209], v[72:75]
	v_mfma_f32_16x16x32_bf16 v[72:75], v[176:179], v[210:213], v[72:75]
	s_barrier
	s_add_i32 s52, 0, 0x1c000
	s_add_i32 s46, s92, s54
	v_add_u32_e32 v157, s52, v139
	v_lshl_add_u64 v[230:231], v[230:231], 0, s[10:11]
	s_mov_b32 m0, s46
	ds_read_b128 v[214:217], v157
	ds_read_b128 v[218:221], v157 offset:1024
	ds_read_b128 v[222:225], v157 offset:2048
	ds_read_b128 v[226:229], v157 offset:3072
	global_load_lds_dwordx4 v[230:231], off
	v_lshl_add_u64 v[230:231], v[232:233], 0, s[10:11]
	s_add_i32 m0, s46, 0x2000
	s_nop 0
	global_load_lds_dwordx4 v[230:231], off
	s_barrier
	s_waitcnt lgkmcnt(0)
	s_waitcnt lgkmcnt(0)
	v_mfma_f32_16x16x32_bf16 v[116:119], v[214:217], v[180:183], v[116:119]
	v_mfma_f32_16x16x32_bf16 v[116:119], v[218:221], v[186:189], v[116:119]
	v_mfma_f32_16x16x32_bf16 v[112:115], v[222:225], v[180:183], v[112:115]
	v_mfma_f32_16x16x32_bf16 v[112:115], v[226:229], v[186:189], v[112:115]
	v_mfma_f32_16x16x32_bf16 v[100:103], v[214:217], v[190:193], v[100:103]
	v_mfma_f32_16x16x32_bf16 v[100:103], v[218:221], v[194:197], v[100:103]
	v_mfma_f32_16x16x32_bf16 v[96:99], v[222:225], v[190:193], v[96:99]
	v_mfma_f32_16x16x32_bf16 v[96:99], v[226:229], v[194:197], v[96:99]
	v_mfma_f32_16x16x32_bf16 v[84:87], v[214:217], v[198:201], v[84:87]
	v_mfma_f32_16x16x32_bf16 v[84:87], v[218:221], v[202:205], v[84:87]
	v_mfma_f32_16x16x32_bf16 v[80:83], v[222:225], v[198:201], v[80:83]
	v_mfma_f32_16x16x32_bf16 v[80:83], v[226:229], v[202:205], v[80:83]
	v_mfma_f32_16x16x32_bf16 v[68:71], v[214:217], v[206:209], v[68:71]
	v_mfma_f32_16x16x32_bf16 v[68:71], v[218:221], v[210:213], v[68:71]
	v_mfma_f32_16x16x32_bf16 v[64:67], v[222:225], v[206:209], v[64:67]
	v_mfma_f32_16x16x32_bf16 v[64:67], v[226:229], v[210:213], v[64:67]
	s_mov_b32 m0, s77
	v_lshl_add_u64 v[230:231], v[234:235], 0, s[10:11]
	s_barrier
	ds_read_b128 v[180:183], v153 offset:49152
	ds_read_b128 v[186:189], v153 offset:50176
	ds_read_b128 v[190:193], v153 offset:51200
	ds_read_b128 v[194:197], v153 offset:52224
	ds_read_b128 v[198:201], v153 offset:53248
	ds_read_b128 v[202:205], v153 offset:54272
	ds_read_b128 v[206:209], v153 offset:55296
	ds_read_b128 v[210:213], v153 offset:56320
	global_load_lds_dwordx4 v[230:231], off
	v_lshl_add_u64 v[230:231], v[236:237], 0, s[10:11]
	s_mov_b32 m0, s78
	s_nop 0
	global_load_lds_dwordx4 v[230:231], off
	s_barrier
	s_waitcnt lgkmcnt(0)
	s_waitcnt lgkmcnt(0)
	v_mfma_f32_16x16x32_bf16 v[60:63], v[160:163], v[180:183], v[60:63]
	v_mfma_f32_16x16x32_bf16 v[60:63], v[164:167], v[186:189], v[60:63]
	v_mfma_f32_16x16x32_bf16 v[56:59], v[168:171], v[180:183], v[56:59]
	v_mfma_f32_16x16x32_bf16 v[56:59], v[176:179], v[186:189], v[56:59]
	v_mfma_f32_16x16x32_bf16 v[48:51], v[160:163], v[190:193], v[48:51]
	v_mfma_f32_16x16x32_bf16 v[48:51], v[164:167], v[194:197], v[48:51]
	v_mfma_f32_16x16x32_bf16 v[40:43], v[168:171], v[190:193], v[40:43]
	v_mfma_f32_16x16x32_bf16 v[40:43], v[176:179], v[194:197], v[40:43]
	v_mfma_f32_16x16x32_bf16 v[32:35], v[160:163], v[198:201], v[32:35]
	v_mfma_f32_16x16x32_bf16 v[32:35], v[164:167], v[202:205], v[32:35]
	v_mfma_f32_16x16x32_bf16 v[24:27], v[168:171], v[198:201], v[24:27]
	v_mfma_f32_16x16x32_bf16 v[24:27], v[176:179], v[202:205], v[24:27]
	v_mfma_f32_16x16x32_bf16 v[16:19], v[160:163], v[206:209], v[16:19]
	v_mfma_f32_16x16x32_bf16 v[16:19], v[164:167], v[210:213], v[16:19]
	v_mfma_f32_16x16x32_bf16 v[8:11], v[168:171], v[206:209], v[8:11]
	v_mfma_f32_16x16x32_bf16 v[8:11], v[176:179], v[210:213], v[8:11]
	s_barrier
	s_add_u32 s46, s50, 0x20080
	s_addc_u32 s47, s51, 0
	s_add_i32 s50, s52, s54
	v_lshl_add_u64 v[160:161], s[46:47], 0, v[130:131]
	s_mov_b32 m0, s50
	s_nop 0
	global_load_lds_dwordx4 v[160:161], off
	v_lshl_add_u64 v[160:161], s[46:47], 0, v[134:135]
	s_add_i32 m0, s50, 0x2000
	s_nop 0
	global_load_lds_dwordx4 v[160:161], off
	s_waitcnt vmcnt(6)
	s_barrier
	v_mfma_f32_16x16x32_bf16 v[52:55], v[214:217], v[180:183], v[52:55]
	v_mfma_f32_16x16x32_bf16 v[52:55], v[218:221], v[186:189], v[52:55]
	v_mfma_f32_16x16x32_bf16 v[44:47], v[222:225], v[180:183], v[44:47]
	v_mfma_f32_16x16x32_bf16 v[44:47], v[226:229], v[186:189], v[44:47]
	v_mfma_f32_16x16x32_bf16 v[36:39], v[214:217], v[190:193], v[36:39]
	v_mfma_f32_16x16x32_bf16 v[36:39], v[218:221], v[194:197], v[36:39]
	v_mfma_f32_16x16x32_bf16 v[28:31], v[222:225], v[190:193], v[28:31]
	v_mfma_f32_16x16x32_bf16 v[28:31], v[226:229], v[194:197], v[28:31]
	v_mfma_f32_16x16x32_bf16 v[20:23], v[214:217], v[198:201], v[20:23]
	v_mfma_f32_16x16x32_bf16 v[20:23], v[218:221], v[202:205], v[20:23]
	v_mfma_f32_16x16x32_bf16 v[12:15], v[222:225], v[198:201], v[12:15]
	v_mfma_f32_16x16x32_bf16 v[12:15], v[226:229], v[202:205], v[12:15]
	v_mfma_f32_16x16x32_bf16 v[4:7], v[214:217], v[206:209], v[4:7]
	v_mfma_f32_16x16x32_bf16 v[4:7], v[218:221], v[210:213], v[4:7]
	v_mfma_f32_16x16x32_bf16 v[0:3], v[222:225], v[206:209], v[0:3]
	v_mfma_f32_16x16x32_bf16 v[0:3], v[226:229], v[210:213], v[0:3]
	s_add_i32 s91, s91, 2
	s_add_u32 s63, s63, 0x100
	s_addc_u32 s90, s90, 0
	s_cmp_gt_u32 s91, 5
	s_mov_b64 s[46:47], s[48:49]
	s_barrier
	s_cbranch_scc0 .LBB0_325
	v_lshl_add_u32 v162, s88, 8, v137
	v_lshl_or_b32 v160, s89, 8, v141
	v_ashrrev_i32_e32 v163, 31, v162
	v_ashrrev_i32_e32 v161, 31, v160
	v_lshlrev_b64 v[164:165], 14, v[162:163]
	v_lshl_add_u64 v[164:165], s[56:57], 0, v[164:165]
	v_lshlrev_b64 v[166:167], 1, v[160:161]
	v_lshl_add_u64 v[160:161], v[164:165], 0, v[166:167]
	s_waitcnt vmcnt(0)
	v_pk_mul_f32 v[126:127], v[158:159], v[126:127] op_sel_hi:[0,1]
	v_pk_mul_f32 v[124:125], v[158:159], v[124:125] op_sel_hi:[0,1]
	v_pk_mul_f32 v[164:165], v[158:159], v[122:123] op_sel_hi:[0,1]
	v_pk_mul_f32 v[122:123], v[158:159], v[120:121] op_sel_hi:[0,1]
	v_cvt_pk_bf16_f32 v120, v124, v125
	v_cvt_pk_bf16_f32 v121, v126, v127
	v_cvt_pk_bf16_f32 v122, v122, v123
	v_cvt_pk_bf16_f32 v123, v164, v165
	global_store_dwordx4 v[160:161], v[120:123], off
	v_pk_mul_f32 v[116:117], v[158:159], v[116:117] op_sel_hi:[0,1]
	v_pk_mul_f32 v[118:119], v[158:159], v[118:119] op_sel_hi:[0,1]
	v_pk_mul_f32 v[120:121], v[158:159], v[114:115] op_sel_hi:[0,1]
	v_pk_mul_f32 v[114:115], v[158:159], v[112:113] op_sel_hi:[0,1]
	v_cvt_pk_bf16_f32 v112, v116, v117
	v_cvt_pk_bf16_f32 v113, v118, v119
	v_cvt_pk_bf16_f32 v114, v114, v115
	v_cvt_pk_bf16_f32 v115, v120, v121
	global_store_dwordx4 v[160:161], v[112:115], off offset:256
	v_pk_mul_f32 v[110:111], v[156:157], v[110:111] op_sel_hi:[0,1]
	v_pk_mul_f32 v[108:109], v[156:157], v[108:109] op_sel_hi:[0,1]
	v_or_b32_e32 v112, 16, v162
	v_ashrrev_i32_e32 v113, 31, v112
	v_lshlrev_b64 v[112:113], 14, v[112:113]
	v_lshl_add_u64 v[112:113], s[56:57], 0, v[112:113]
	v_lshl_add_u64 v[112:113], v[112:113], 0, v[166:167]
	v_pk_mul_f32 v[114:115], v[156:157], v[106:107] op_sel_hi:[0,1]
	v_pk_mul_f32 v[106:107], v[156:157], v[104:105] op_sel_hi:[0,1]
	v_cvt_pk_bf16_f32 v104, v108, v109
	v_cvt_pk_bf16_f32 v105, v110, v111
	v_cvt_pk_bf16_f32 v106, v106, v107
	v_cvt_pk_bf16_f32 v107, v114, v115
	global_store_dwordx4 v[112:113], v[104:107], off
	v_pk_mul_f32 v[100:101], v[156:157], v[100:101] op_sel_hi:[0,1]
	v_pk_mul_f32 v[102:103], v[156:157], v[102:103] op_sel_hi:[0,1]
	v_pk_mul_f32 v[104:105], v[156:157], v[98:99] op_sel_hi:[0,1]
	v_pk_mul_f32 v[98:99], v[156:157], v[96:97] op_sel_hi:[0,1]
	v_cvt_pk_bf16_f32 v96, v100, v101
	v_cvt_pk_bf16_f32 v97, v102, v103
	v_cvt_pk_bf16_f32 v98, v98, v99
	v_cvt_pk_bf16_f32 v99, v104, v105
	global_store_dwordx4 v[112:113], v[96:99], off offset:256
	v_pk_mul_f32 v[94:95], v[154:155], v[94:95] op_sel_hi:[0,1]
	v_pk_mul_f32 v[92:93], v[154:155], v[92:93] op_sel_hi:[0,1]
	v_or_b32_e32 v96, 32, v162
	v_ashrrev_i32_e32 v97, 31, v96
	v_lshlrev_b64 v[96:97], 14, v[96:97]
	v_lshl_add_u64 v[96:97], s[56:57], 0, v[96:97]
	v_lshl_add_u64 v[96:97], v[96:97], 0, v[166:167]
	v_pk_mul_f32 v[98:99], v[154:155], v[90:91] op_sel_hi:[0,1]
	v_pk_mul_f32 v[90:91], v[154:155], v[88:89] op_sel_hi:[0,1]
	v_cvt_pk_bf16_f32 v88, v92, v93
	v_cvt_pk_bf16_f32 v89, v94, v95
	v_cvt_pk_bf16_f32 v90, v90, v91
	v_cvt_pk_bf16_f32 v91, v98, v99
	global_store_dwordx4 v[96:97], v[88:91], off
	v_pk_mul_f32 v[84:85], v[154:155], v[84:85] op_sel_hi:[0,1]
	v_pk_mul_f32 v[86:87], v[154:155], v[86:87] op_sel_hi:[0,1]
	v_pk_mul_f32 v[88:89], v[154:155], v[82:83] op_sel_hi:[0,1]
	v_pk_mul_f32 v[82:83], v[154:155], v[80:81] op_sel_hi:[0,1]
	v_cvt_pk_bf16_f32 v80, v84, v85
	v_cvt_pk_bf16_f32 v81, v86, v87
	v_cvt_pk_bf16_f32 v82, v82, v83
	v_cvt_pk_bf16_f32 v83, v88, v89
	global_store_dwordx4 v[96:97], v[80:83], off offset:256
	v_pk_mul_f32 v[78:79], v[152:153], v[78:79] op_sel_hi:[0,1]
	v_pk_mul_f32 v[76:77], v[152:153], v[76:77] op_sel_hi:[0,1]
	v_or_b32_e32 v80, 48, v162
	v_ashrrev_i32_e32 v81, 31, v80
	v_lshlrev_b64 v[80:81], 14, v[80:81]
	v_lshl_add_u64 v[80:81], s[56:57], 0, v[80:81]
	v_lshl_add_u64 v[80:81], v[80:81], 0, v[166:167]
	v_pk_mul_f32 v[82:83], v[152:153], v[74:75] op_sel_hi:[0,1]
	v_pk_mul_f32 v[74:75], v[152:153], v[72:73] op_sel_hi:[0,1]
	v_cvt_pk_bf16_f32 v72, v76, v77
	v_cvt_pk_bf16_f32 v73, v78, v79
	v_cvt_pk_bf16_f32 v74, v74, v75
	v_cvt_pk_bf16_f32 v75, v82, v83
	global_store_dwordx4 v[80:81], v[72:75], off
	v_pk_mul_f32 v[70:71], v[152:153], v[70:71] op_sel_hi:[0,1]
	v_pk_mul_f32 v[68:69], v[152:153], v[68:69] op_sel_hi:[0,1]
	v_pk_mul_f32 v[72:73], v[152:153], v[66:67] op_sel_hi:[0,1]
	v_pk_mul_f32 v[66:67], v[152:153], v[64:65] op_sel_hi:[0,1]
	v_cvt_pk_bf16_f32 v64, v68, v69
	v_cvt_pk_bf16_f32 v65, v70, v71
	v_cvt_pk_bf16_f32 v66, v66, v67
	v_cvt_pk_bf16_f32 v67, v72, v73
	v_pk_mul_f32 v[60:61], v[150:151], v[60:61] op_sel_hi:[0,1]
	global_store_dwordx4 v[80:81], v[64:67], off offset:256
	v_pk_mul_f32 v[62:63], v[150:151], v[62:63] op_sel_hi:[0,1]
	s_mov_b64 s[46:47], 0x200000
	v_pk_mul_f32 v[66:67], v[150:151], v[58:59] op_sel_hi:[0,1]
	v_pk_mul_f32 v[58:59], v[150:151], v[56:57] op_sel_hi:[0,1]
	v_cvt_pk_bf16_f32 v56, v60, v61
	v_add_co_u32_e32 v60, vcc, s83, v160
	v_cvt_pk_bf16_f32 v57, v62, v63
	v_cvt_pk_bf16_f32 v58, v58, v59
	v_cvt_pk_bf16_f32 v59, v66, v67
	v_lshl_add_u64 v[64:65], v[160:161], 0, s[46:47]
	s_nop 0
	v_addc_co_u32_e32 v61, vcc, 0, v161, vcc
	global_store_dwordx4 v[60:61], v[56:59], off
	v_pk_mul_f32 v[54:55], v[150:151], v[54:55] op_sel_hi:[0,1]
	v_pk_mul_f32 v[52:53], v[150:151], v[52:53] op_sel_hi:[0,1]
	v_pk_mul_f32 v[56:57], v[150:151], v[46:47] op_sel_hi:[0,1]
	v_pk_mul_f32 v[46:47], v[150:151], v[44:45] op_sel_hi:[0,1]
	v_cvt_pk_bf16_f32 v44, v52, v53
	v_cvt_pk_bf16_f32 v45, v54, v55
	v_cvt_pk_bf16_f32 v46, v46, v47
	v_cvt_pk_bf16_f32 v47, v56, v57
	global_store_dwordx4 v[64:65], v[44:47], off offset:256
	v_pk_mul_f32 v[48:49], v[140:141], v[48:49] op_sel_hi:[0,1]
	v_pk_mul_f32 v[38:39], v[140:141], v[38:39] op_sel_hi:[0,1]
	v_pk_mul_f32 v[46:47], v[140:141], v[50:51] op_sel_hi:[0,1]
	v_pk_mul_f32 v[50:51], v[140:141], v[42:43] op_sel_hi:[0,1]
	v_pk_mul_f32 v[42:43], v[140:141], v[40:41] op_sel_hi:[0,1]
	v_cvt_pk_bf16_f32 v40, v48, v49
	v_cvt_pk_bf16_f32 v41, v46, v47
	v_add_co_u32_e32 v46, vcc, s84, v160
	v_cvt_pk_bf16_f32 v42, v42, v43
	v_cvt_pk_bf16_f32 v43, v50, v51
	v_lshl_add_u64 v[44:45], v[160:161], 0, s[30:31]
	s_nop 0
	v_addc_co_u32_e32 v47, vcc, 0, v161, vcc
	global_store_dwordx4 v[46:47], v[40:43], off
	v_pk_mul_f32 v[36:37], v[140:141], v[36:37] op_sel_hi:[0,1]
	v_pk_mul_f32 v[32:33], v[138:139], v[32:33] op_sel_hi:[0,1]
	v_pk_mul_f32 v[40:41], v[140:141], v[30:31] op_sel_hi:[0,1]
	v_pk_mul_f32 v[30:31], v[140:141], v[28:29] op_sel_hi:[0,1]
	v_cvt_pk_bf16_f32 v28, v36, v37
	v_cvt_pk_bf16_f32 v29, v38, v39
	v_cvt_pk_bf16_f32 v30, v30, v31
	v_cvt_pk_bf16_f32 v31, v40, v41
	global_store_dwordx4 v[44:45], v[28:31], off offset:256
	v_pk_mul_f32 v[22:23], v[138:139], v[22:23] op_sel_hi:[0,1]
	v_pk_mul_f32 v[20:21], v[138:139], v[20:21] op_sel_hi:[0,1]
	v_pk_mul_f32 v[30:31], v[138:139], v[34:35] op_sel_hi:[0,1]
	v_pk_mul_f32 v[34:35], v[138:139], v[26:27] op_sel_hi:[0,1]
	v_pk_mul_f32 v[26:27], v[138:139], v[24:25] op_sel_hi:[0,1]
	v_cvt_pk_bf16_f32 v24, v32, v33
	v_cvt_pk_bf16_f32 v25, v30, v31
	v_add_co_u32_e32 v30, vcc, s85, v160
	v_cvt_pk_bf16_f32 v26, v26, v27
	v_cvt_pk_bf16_f32 v27, v34, v35
	v_lshl_add_u64 v[28:29], v[160:161], 0, s[36:37]
	s_nop 0
	v_addc_co_u32_e32 v31, vcc, 0, v161, vcc
	global_store_dwordx4 v[30:31], v[24:27], off
	v_pk_mul_f32 v[16:17], v[136:137], v[16:17] op_sel_hi:[0,1]
	s_mov_b64 s[46:47], -1
	v_pk_mul_f32 v[24:25], v[138:139], v[14:15] op_sel_hi:[0,1]
	v_pk_mul_f32 v[14:15], v[138:139], v[12:13] op_sel_hi:[0,1]
	v_cvt_pk_bf16_f32 v12, v20, v21
	v_cvt_pk_bf16_f32 v13, v22, v23
	v_cvt_pk_bf16_f32 v14, v14, v15
	v_cvt_pk_bf16_f32 v15, v24, v25
	global_store_dwordx4 v[28:29], v[12:15], off offset:256
	v_pk_mul_f32 v[6:7], v[136:137], v[6:7] op_sel_hi:[0,1]
	v_pk_mul_f32 v[4:5], v[136:137], v[4:5] op_sel_hi:[0,1]
	v_pk_mul_f32 v[14:15], v[136:137], v[18:19] op_sel_hi:[0,1]
	v_pk_mul_f32 v[18:19], v[136:137], v[10:11] op_sel_hi:[0,1]
	v_pk_mul_f32 v[10:11], v[136:137], v[8:9] op_sel_hi:[0,1]
	v_cvt_pk_bf16_f32 v8, v16, v17
	v_cvt_pk_bf16_f32 v9, v14, v15
	v_add_co_u32_e32 v14, vcc, s86, v160
	v_lshl_add_u64 v[12:13], v[160:161], 0, s[38:39]
	s_nop 0
	v_addc_co_u32_e32 v15, vcc, 0, v161, vcc
	v_cvt_pk_bf16_f32 v10, v10, v11
	v_cvt_pk_bf16_f32 v11, v18, v19
	global_store_dwordx4 v[14:15], v[8:11], off
	s_and_b64 vcc, s[8:9], exec
	s_nop 0
	v_pk_mul_f32 v[8:9], v[136:137], v[2:3] op_sel_hi:[0,1]
	v_pk_mul_f32 v[2:3], v[136:137], v[0:1] op_sel_hi:[0,1]
	v_cvt_pk_bf16_f32 v0, v4, v5
	v_cvt_pk_bf16_f32 v1, v6, v7
	v_cvt_pk_bf16_f32 v2, v2, v3
	v_cvt_pk_bf16_f32 v3, v8, v9
	global_store_dwordx4 v[12:13], v[0:3], off offset:256
	s_cbranch_vccz .LBB0_315
	s_nop 0
	v_lshl_add_u32 v0, s87, 8, v137
	v_ashrrev_i32_e32 v1, 31, v0
	v_lshl_add_u64 v[0:1], v[0:1], 2, s[34:35]
	global_load_dword v158, v[0:1], off
	global_load_dword v156, v[0:1], off offset:64
	global_load_dword v154, v[0:1], off offset:128
	global_load_dword v152, v[0:1], off offset:192
	global_load_dword v150, v[0:1], off offset:512
	global_load_dword v140, v[0:1], off offset:576
	global_load_dword v138, v[0:1], off offset:640
	global_load_dword v136, v[0:1], off offset:704
	s_mov_b64 s[46:47], 0
	s_branch .LBB0_315

.Lh1_first:
	s_setprio 0
	s_cmp_gt_u32 s96, 3
	s_cbranch_scc1 .Lprio_skip
	s_setprio 1

.LBB0_420:
	s_setprio 0
	s_cmp_lt_u32 s99, 0x100
	s_cbranch_scc1 .Lgp_att
	s_setprio 1

.LBB0_514:
	ds_read_b128 v[128:131], v171
	ds_read_b128 v[132:135], v171 offset:1024
	ds_read_b128 v[136:139], v171 offset:2048
	ds_read_b128 v[140:143], v171 offset:3072
	s_add_u32 s40, s38, 0xfff00080
	s_addc_u32 s41, s39, -1
	s_cmp_eq_u32 s61, 60
	s_cselect_b32 s43, s6, s41
	s_cselect_b32 s42, s7, s40
	s_cselect_b32 s41, s25, s55
	s_cselect_b32 s40, s27, s35
	v_lshl_add_u64 v[202:203], s[38:39], 0, v[152:153]
	s_add_i32 m0, s37, 0xc000
	ds_read_b128 v[160:163], v173
	ds_read_b128 v[164:167], v173 offset:1024
	ds_read_b128 v[176:179], v173 offset:2048
	ds_read_b128 v[180:183], v173 offset:3072
	ds_read_b128 v[186:189], v173 offset:4096
	ds_read_b128 v[190:193], v173 offset:5120
	ds_read_b128 v[194:197], v173 offset:6144
	ds_read_b128 v[198:201], v173 offset:7168
	global_load_lds_dwordx4 v[202:203], off
	v_lshl_add_u64 v[202:203], s[38:39], 0, v[154:155]
	s_add_i32 m0, s37, 0xe000
	s_nop 0
	global_load_lds_dwordx4 v[202:203], off
	s_waitcnt lgkmcnt(8)
	s_barrier
	s_waitcnt lgkmcnt(0)
	s_waitcnt lgkmcnt(0)
	v_mfma_f32_16x16x32_bf16 v[124:127], v[128:131], v[160:163], v[124:127]
	v_mfma_f32_16x16x32_bf16 v[124:127], v[132:135], v[164:167], v[124:127]
	v_mfma_f32_16x16x32_bf16 v[120:123], v[136:139], v[160:163], v[120:123]
	v_mfma_f32_16x16x32_bf16 v[120:123], v[140:143], v[164:167], v[120:123]
	v_mfma_f32_16x16x32_bf16 v[108:111], v[128:131], v[176:179], v[108:111]
	v_mfma_f32_16x16x32_bf16 v[108:111], v[132:135], v[180:183], v[108:111]
	v_mfma_f32_16x16x32_bf16 v[104:107], v[136:139], v[176:179], v[104:107]
	v_mfma_f32_16x16x32_bf16 v[104:107], v[140:143], v[180:183], v[104:107]
	v_mfma_f32_16x16x32_bf16 v[92:95], v[128:131], v[186:189], v[92:95]
	v_mfma_f32_16x16x32_bf16 v[92:95], v[132:135], v[190:193], v[92:95]
	v_mfma_f32_16x16x32_bf16 v[88:91], v[136:139], v[186:189], v[88:91]
	v_mfma_f32_16x16x32_bf16 v[88:91], v[140:143], v[190:193], v[88:91]
	v_mfma_f32_16x16x32_bf16 v[76:79], v[128:131], v[194:197], v[76:79]
	v_mfma_f32_16x16x32_bf16 v[76:79], v[132:135], v[198:201], v[76:79]
	v_mfma_f32_16x16x32_bf16 v[72:75], v[136:139], v[194:197], v[72:75]
	v_mfma_f32_16x16x32_bf16 v[72:75], v[140:143], v[198:201], v[72:75]
	s_barrier
	s_add_i32 s62, s53, s5
	v_lshl_add_u64 v[218:219], s[40:41], 0, v[146:147]
	s_mov_b32 m0, s62
	ds_read_b128 v[202:205], v174
	ds_read_b128 v[206:209], v174 offset:1024
	ds_read_b128 v[210:213], v174 offset:2048
	ds_read_b128 v[214:217], v174 offset:3072
	global_load_lds_dwordx4 v[218:219], off
	v_lshl_add_u64 v[220:221], s[40:41], 0, v[150:151]
	s_add_i32 m0, s62, 0x2000
	s_nop 0
	global_load_lds_dwordx4 v[220:221], off
	s_barrier
	s_waitcnt lgkmcnt(0)
	s_waitcnt lgkmcnt(0)
	v_mfma_f32_16x16x32_bf16 v[116:119], v[202:205], v[160:163], v[116:119]
	v_mfma_f32_16x16x32_bf16 v[116:119], v[206:209], v[164:167], v[116:119]
	v_mfma_f32_16x16x32_bf16 v[112:115], v[210:213], v[160:163], v[112:115]
	v_mfma_f32_16x16x32_bf16 v[112:115], v[214:217], v[164:167], v[112:115]
	v_mfma_f32_16x16x32_bf16 v[100:103], v[202:205], v[176:179], v[100:103]
	v_mfma_f32_16x16x32_bf16 v[100:103], v[206:209], v[180:183], v[100:103]
	v_mfma_f32_16x16x32_bf16 v[96:99], v[210:213], v[176:179], v[96:99]
	v_mfma_f32_16x16x32_bf16 v[96:99], v[214:217], v[180:183], v[96:99]
	v_mfma_f32_16x16x32_bf16 v[84:87], v[202:205], v[186:189], v[84:87]
	v_mfma_f32_16x16x32_bf16 v[84:87], v[206:209], v[190:193], v[84:87]
	v_mfma_f32_16x16x32_bf16 v[80:83], v[210:213], v[186:189], v[80:83]
	v_mfma_f32_16x16x32_bf16 v[80:83], v[214:217], v[190:193], v[80:83]
	v_mfma_f32_16x16x32_bf16 v[68:71], v[202:205], v[194:197], v[68:71]
	v_mfma_f32_16x16x32_bf16 v[68:71], v[206:209], v[198:201], v[68:71]
	v_mfma_f32_16x16x32_bf16 v[64:67], v[210:213], v[194:197], v[64:67]
	v_mfma_f32_16x16x32_bf16 v[64:67], v[214:217], v[198:201], v[64:67]
	s_mov_b32 m0, s37
	v_lshl_add_u64 v[222:223], s[42:43], 0, v[144:145]
	s_barrier
	ds_read_b128 v[160:163], v173 offset:16384
	ds_read_b128 v[164:167], v173 offset:17408
	ds_read_b128 v[176:179], v173 offset:18432
	ds_read_b128 v[180:183], v173 offset:19456
	ds_read_b128 v[186:189], v173 offset:20480
	ds_read_b128 v[190:193], v173 offset:21504
	ds_read_b128 v[194:197], v173 offset:22528
	ds_read_b128 v[198:201], v173 offset:23552
	global_load_lds_dwordx4 v[222:223], off
	v_lshl_add_u64 v[224:225], s[42:43], 0, v[148:149]
	s_mov_b32 m0, s44
	s_nop 0
	global_load_lds_dwordx4 v[224:225], off
	s_barrier
	s_waitcnt lgkmcnt(0)
	s_waitcnt lgkmcnt(0)
	v_mfma_f32_16x16x32_bf16 v[60:63], v[128:131], v[160:163], v[60:63]
	v_mfma_f32_16x16x32_bf16 v[60:63], v[132:135], v[164:167], v[60:63]
	v_mfma_f32_16x16x32_bf16 v[56:59], v[136:139], v[160:163], v[56:59]
	v_mfma_f32_16x16x32_bf16 v[56:59], v[140:143], v[164:167], v[56:59]
	v_mfma_f32_16x16x32_bf16 v[44:47], v[128:131], v[176:179], v[44:47]
	v_mfma_f32_16x16x32_bf16 v[44:47], v[132:135], v[180:183], v[44:47]
	v_mfma_f32_16x16x32_bf16 v[40:43], v[136:139], v[176:179], v[40:43]
	v_mfma_f32_16x16x32_bf16 v[40:43], v[140:143], v[180:183], v[40:43]
	v_mfma_f32_16x16x32_bf16 v[28:31], v[128:131], v[186:189], v[28:31]
	v_mfma_f32_16x16x32_bf16 v[28:31], v[132:135], v[190:193], v[28:31]
	v_mfma_f32_16x16x32_bf16 v[24:27], v[136:139], v[186:189], v[24:27]
	v_mfma_f32_16x16x32_bf16 v[24:27], v[140:143], v[190:193], v[24:27]
	v_mfma_f32_16x16x32_bf16 v[12:15], v[128:131], v[194:197], v[12:15]
	v_mfma_f32_16x16x32_bf16 v[12:15], v[132:135], v[198:201], v[12:15]
	v_mfma_f32_16x16x32_bf16 v[8:11], v[136:139], v[194:197], v[8:11]
	v_mfma_f32_16x16x32_bf16 v[8:11], v[140:143], v[198:201], v[8:11]
	s_barrier
	s_add_u32 s62, s40, 0x100000
	s_addc_u32 s63, s41, 0
	s_add_i32 s74, s54, s5
	v_lshl_add_u64 v[128:129], s[62:63], 0, v[146:147]
	s_mov_b32 m0, s74
	s_nop 0
	global_load_lds_dwordx4 v[128:129], off
	v_lshl_add_u64 v[128:129], s[62:63], 0, v[150:151]
	s_add_i32 m0, s74, 0x2000
	s_nop 0
	global_load_lds_dwordx4 v[128:129], off
	s_waitcnt vmcnt(6)
	s_barrier
	v_mfma_f32_16x16x32_bf16 v[52:55], v[202:205], v[160:163], v[52:55]
	v_mfma_f32_16x16x32_bf16 v[52:55], v[206:209], v[164:167], v[52:55]
	v_mfma_f32_16x16x32_bf16 v[48:51], v[210:213], v[160:163], v[48:51]
	v_mfma_f32_16x16x32_bf16 v[48:51], v[214:217], v[164:167], v[48:51]
	v_mfma_f32_16x16x32_bf16 v[36:39], v[202:205], v[176:179], v[36:39]
	v_mfma_f32_16x16x32_bf16 v[36:39], v[206:209], v[180:183], v[36:39]
	v_mfma_f32_16x16x32_bf16 v[32:35], v[210:213], v[176:179], v[32:35]
	v_mfma_f32_16x16x32_bf16 v[32:35], v[214:217], v[180:183], v[32:35]
	v_mfma_f32_16x16x32_bf16 v[20:23], v[202:205], v[186:189], v[20:23]
	v_mfma_f32_16x16x32_bf16 v[20:23], v[206:209], v[190:193], v[20:23]
	v_mfma_f32_16x16x32_bf16 v[16:19], v[210:213], v[186:189], v[16:19]
	v_mfma_f32_16x16x32_bf16 v[16:19], v[214:217], v[190:193], v[16:19]
	v_mfma_f32_16x16x32_bf16 v[4:7], v[202:205], v[194:197], v[4:7]
	v_mfma_f32_16x16x32_bf16 v[4:7], v[206:209], v[198:201], v[4:7]
	v_mfma_f32_16x16x32_bf16 v[0:3], v[210:213], v[194:197], v[0:3]
	v_mfma_f32_16x16x32_bf16 v[0:3], v[214:217], v[198:201], v[0:3]
	s_add_i32 s62, 0, 0x18000
	v_add_u32_e32 v140, s62, v169
	s_barrier
	ds_read_b128 v[128:131], v140
	ds_read_b128 v[132:135], v140 offset:1024
	ds_read_b128 v[136:139], v140 offset:2048
	ds_read_b128 v[140:143], v140 offset:3072
	s_add_u32 s42, s42, 0x100000
	s_addc_u32 s43, s43, 0
	s_mov_b32 m0, s45
	v_lshl_add_u64 v[202:203], s[42:43], 0, v[144:145]
	ds_read_b128 v[160:163], v173 offset:32768
	ds_read_b128 v[164:167], v173 offset:33792
	ds_read_b128 v[176:179], v173 offset:34816
	ds_read_b128 v[180:183], v173 offset:35840
	ds_read_b128 v[186:189], v173 offset:36864
	ds_read_b128 v[190:193], v173 offset:37888
	ds_read_b128 v[194:197], v173 offset:38912
	ds_read_b128 v[198:201], v173 offset:39936
	global_load_lds_dwordx4 v[202:203], off
	v_lshl_add_u64 v[202:203], s[42:43], 0, v[148:149]
	s_mov_b32 m0, s46
	s_nop 0
	global_load_lds_dwordx4 v[202:203], off
	s_waitcnt lgkmcnt(8)
	s_barrier
	s_waitcnt lgkmcnt(0)
	s_waitcnt lgkmcnt(0)
	v_mfma_f32_16x16x32_bf16 v[124:127], v[128:131], v[160:163], v[124:127]
	v_mfma_f32_16x16x32_bf16 v[124:127], v[132:135], v[164:167], v[124:127]
	v_mfma_f32_16x16x32_bf16 v[120:123], v[136:139], v[160:163], v[120:123]
	v_mfma_f32_16x16x32_bf16 v[120:123], v[140:143], v[164:167], v[120:123]
	v_mfma_f32_16x16x32_bf16 v[108:111], v[128:131], v[176:179], v[108:111]
	v_mfma_f32_16x16x32_bf16 v[108:111], v[132:135], v[180:183], v[108:111]
	v_mfma_f32_16x16x32_bf16 v[104:107], v[136:139], v[176:179], v[104:107]
	v_mfma_f32_16x16x32_bf16 v[104:107], v[140:143], v[180:183], v[104:107]
	v_mfma_f32_16x16x32_bf16 v[92:95], v[128:131], v[186:189], v[92:95]
	v_mfma_f32_16x16x32_bf16 v[92:95], v[132:135], v[190:193], v[92:95]
	v_mfma_f32_16x16x32_bf16 v[88:91], v[136:139], v[186:189], v[88:91]
	v_mfma_f32_16x16x32_bf16 v[88:91], v[140:143], v[190:193], v[88:91]
	v_mfma_f32_16x16x32_bf16 v[76:79], v[128:131], v[194:197], v[76:79]
	v_mfma_f32_16x16x32_bf16 v[76:79], v[132:135], v[198:201], v[76:79]
	v_mfma_f32_16x16x32_bf16 v[72:75], v[136:139], v[194:197], v[72:75]
	v_mfma_f32_16x16x32_bf16 v[72:75], v[140:143], v[198:201], v[72:75]
	s_barrier
	s_add_i32 s42, 0, 0x1c000
	s_add_i32 s43, s62, s5
	v_add_u32_e32 v185, s42, v169
	v_lshl_add_u64 v[218:219], v[218:219], 0, s[22:23]
	s_mov_b32 m0, s43
	ds_read_b128 v[202:205], v185
	ds_read_b128 v[206:209], v185 offset:1024
	ds_read_b128 v[210:213], v185 offset:2048
	ds_read_b128 v[214:217], v185 offset:3072
	global_load_lds_dwordx4 v[218:219], off
	v_lshl_add_u64 v[218:219], v[220:221], 0, s[22:23]
	s_add_i32 m0, s43, 0x2000
	s_nop 0
	global_load_lds_dwordx4 v[218:219], off
	s_barrier
	s_waitcnt lgkmcnt(0)
	s_waitcnt lgkmcnt(0)
	v_mfma_f32_16x16x32_bf16 v[116:119], v[202:205], v[160:163], v[116:119]
	v_mfma_f32_16x16x32_bf16 v[116:119], v[206:209], v[164:167], v[116:119]
	v_mfma_f32_16x16x32_bf16 v[112:115], v[210:213], v[160:163], v[112:115]
	v_mfma_f32_16x16x32_bf16 v[112:115], v[214:217], v[164:167], v[112:115]
	v_mfma_f32_16x16x32_bf16 v[100:103], v[202:205], v[176:179], v[100:103]
	v_mfma_f32_16x16x32_bf16 v[100:103], v[206:209], v[180:183], v[100:103]
	v_mfma_f32_16x16x32_bf16 v[96:99], v[210:213], v[176:179], v[96:99]
	v_mfma_f32_16x16x32_bf16 v[96:99], v[214:217], v[180:183], v[96:99]
	v_mfma_f32_16x16x32_bf16 v[84:87], v[202:205], v[186:189], v[84:87]
	v_mfma_f32_16x16x32_bf16 v[84:87], v[206:209], v[190:193], v[84:87]
	v_mfma_f32_16x16x32_bf16 v[80:83], v[210:213], v[186:189], v[80:83]
	v_mfma_f32_16x16x32_bf16 v[80:83], v[214:217], v[190:193], v[80:83]
	v_mfma_f32_16x16x32_bf16 v[68:71], v[202:205], v[194:197], v[68:71]
	v_mfma_f32_16x16x32_bf16 v[68:71], v[206:209], v[198:201], v[68:71]
	v_mfma_f32_16x16x32_bf16 v[64:67], v[210:213], v[194:197], v[64:67]
	v_mfma_f32_16x16x32_bf16 v[64:67], v[214:217], v[198:201], v[64:67]
	s_mov_b32 m0, s48
	v_lshl_add_u64 v[218:219], v[222:223], 0, s[22:23]
	s_barrier
	ds_read_b128 v[160:163], v173 offset:49152
	ds_read_b128 v[164:167], v173 offset:50176
	ds_read_b128 v[176:179], v173 offset:51200
	ds_read_b128 v[180:183], v173 offset:52224
	ds_read_b128 v[186:189], v173 offset:53248
	ds_read_b128 v[190:193], v173 offset:54272
	ds_read_b128 v[194:197], v173 offset:55296
	ds_read_b128 v[198:201], v173 offset:56320
	global_load_lds_dwordx4 v[218:219], off
	v_lshl_add_u64 v[218:219], v[224:225], 0, s[22:23]
	s_mov_b32 m0, s49
	s_nop 0
	global_load_lds_dwordx4 v[218:219], off
	s_barrier
	s_waitcnt lgkmcnt(0)
	s_waitcnt lgkmcnt(0)
	v_mfma_f32_16x16x32_bf16 v[60:63], v[128:131], v[160:163], v[60:63]
	v_mfma_f32_16x16x32_bf16 v[60:63], v[132:135], v[164:167], v[60:63]
	v_mfma_f32_16x16x32_bf16 v[56:59], v[136:139], v[160:163], v[56:59]
	v_mfma_f32_16x16x32_bf16 v[56:59], v[140:143], v[164:167], v[56:59]
	v_mfma_f32_16x16x32_bf16 v[44:47], v[128:131], v[176:179], v[44:47]
	v_mfma_f32_16x16x32_bf16 v[44:47], v[132:135], v[180:183], v[44:47]
	v_mfma_f32_16x16x32_bf16 v[40:43], v[136:139], v[176:179], v[40:43]
	v_mfma_f32_16x16x32_bf16 v[40:43], v[140:143], v[180:183], v[40:43]
	v_mfma_f32_16x16x32_bf16 v[28:31], v[128:131], v[186:189], v[28:31]
	v_mfma_f32_16x16x32_bf16 v[28:31], v[132:135], v[190:193], v[28:31]
	v_mfma_f32_16x16x32_bf16 v[24:27], v[136:139], v[186:189], v[24:27]
	v_mfma_f32_16x16x32_bf16 v[24:27], v[140:143], v[190:193], v[24:27]
	v_mfma_f32_16x16x32_bf16 v[12:15], v[128:131], v[194:197], v[12:15]
	v_mfma_f32_16x16x32_bf16 v[12:15], v[132:135], v[198:201], v[12:15]
	v_mfma_f32_16x16x32_bf16 v[8:11], v[136:139], v[194:197], v[8:11]
	v_mfma_f32_16x16x32_bf16 v[8:11], v[140:143], v[198:201], v[8:11]
	s_barrier
	s_add_u32 s40, s40, 0x100080
	s_addc_u32 s41, s41, 0
	s_add_i32 s42, s42, s5
	v_lshl_add_u64 v[128:129], s[40:41], 0, v[146:147]
	s_mov_b32 m0, s42
	s_nop 0
	global_load_lds_dwordx4 v[128:129], off
	v_lshl_add_u64 v[128:129], s[40:41], 0, v[150:151]
	s_add_i32 m0, s42, 0x2000
	s_nop 0
	global_load_lds_dwordx4 v[128:129], off
	s_waitcnt vmcnt(6)
	s_barrier
	v_mfma_f32_16x16x32_bf16 v[52:55], v[202:205], v[160:163], v[52:55]
	v_mfma_f32_16x16x32_bf16 v[52:55], v[206:209], v[164:167], v[52:55]
	v_mfma_f32_16x16x32_bf16 v[48:51], v[210:213], v[160:163], v[48:51]
	v_mfma_f32_16x16x32_bf16 v[48:51], v[214:217], v[164:167], v[48:51]
	v_mfma_f32_16x16x32_bf16 v[36:39], v[202:205], v[176:179], v[36:39]
	v_mfma_f32_16x16x32_bf16 v[36:39], v[206:209], v[180:183], v[36:39]
	v_mfma_f32_16x16x32_bf16 v[32:35], v[210:213], v[176:179], v[32:35]
	v_mfma_f32_16x16x32_bf16 v[32:35], v[214:217], v[180:183], v[32:35]
	v_mfma_f32_16x16x32_bf16 v[20:23], v[202:205], v[186:189], v[20:23]
	v_mfma_f32_16x16x32_bf16 v[20:23], v[206:209], v[190:193], v[20:23]
	v_mfma_f32_16x16x32_bf16 v[16:19], v[210:213], v[186:189], v[16:19]
	v_mfma_f32_16x16x32_bf16 v[16:19], v[214:217], v[190:193], v[16:19]
	v_mfma_f32_16x16x32_bf16 v[4:7], v[202:205], v[194:197], v[4:7]
	v_mfma_f32_16x16x32_bf16 v[4:7], v[206:209], v[198:201], v[4:7]
	v_mfma_f32_16x16x32_bf16 v[0:3], v[210:213], v[194:197], v[0:3]
	v_mfma_f32_16x16x32_bf16 v[0:3], v[214:217], v[198:201], v[0:3]
	s_add_i32 s61, s61, 2
	s_add_u32 s38, s38, 0x100
	s_addc_u32 s39, s39, 0
	s_add_u32 s35, s35, 0x100
	s_addc_u32 s55, s55, 0
	s_cmp_gt_u32 s61, 61
	s_barrier
	s_cbranch_scc0 .LBB0_514
	v_lshl_add_u32 v162, s34, 8, v168
	v_lshl_or_b32 v160, s36, 8, v170
	v_ashrrev_i32_e32 v163, 31, v162
	v_ashrrev_i32_e32 v161, 31, v160
	v_lshlrev_b64 v[128:129], 14, v[162:163]
	v_lshl_add_u64 v[128:129], s[12:13], 0, v[128:129]
	v_lshlrev_b64 v[130:131], 2, v[160:161]
	v_lshl_add_u64 v[128:129], v[128:129], 0, v[130:131]
	global_load_dwordx4 v[178:181], v[128:129], off
	global_load_dwordx4 v[186:189], v[128:129], off offset:16
	global_load_dwordx4 v[190:193], v[128:129], off offset:512
	global_load_dwordx4 v[194:197], v[128:129], off offset:528
	v_or_b32_e32 v164, 16, v162
	v_ashrrev_i32_e32 v165, 31, v164
	v_lshlrev_b64 v[128:129], 14, v[164:165]
	v_lshl_add_u64 v[128:129], s[12:13], 0, v[128:129]
	v_lshl_add_u64 v[132:133], v[128:129], 0, v[130:131]
	global_load_dwordx4 v[136:139], v[132:133], off offset:16
	global_load_dwordx4 v[140:143], v[132:133], off
	global_load_dwordx4 v[128:131], v[132:133], off offset:528
	s_nop 0
	global_load_dwordx4 v[132:135], v[132:133], off offset:512
	v_and_b32_e32 v166, 64, v175
	v_xor_b32_e32 v176, 16, v175
	v_add_u32_e32 v182, 64, v166
	v_xor_b32_e32 v177, 32, v175
	v_cmp_lt_i32_e32 vcc, v176, v182
	v_lshlrev_b64 v[166:167], 13, v[162:163]
	v_lshl_add_u64 v[166:167], s[56:57], 0, v[166:167]
	v_cndmask_b32_e32 v176, v175, v176, vcc
	v_cmp_lt_i32_e32 vcc, v177, v182
	v_lshlrev_b32_e32 v176, 2, v176
	v_lshl_add_u64 v[166:167], v[160:161], 1, v[166:167]
	v_cndmask_b32_e32 v177, v175, v177, vcc
	v_lshlrev_b32_e32 v177, 2, v177
	s_waitcnt vmcnt(0)
	v_pk_add_f32 v[126:127], v[126:127], v[180:181]
	v_pk_add_f32 v[124:125], v[124:125], v[178:179]
	v_pk_add_f32 v[118:119], v[118:119], v[192:193]
	v_pk_add_f32 v[116:117], v[116:117], v[190:191]
	v_pk_add_f32 v[120:121], v[120:121], v[186:187]
	v_pk_add_f32 v[178:179], v[114:115], v[196:197]
	v_pk_add_f32 v[180:181], v[112:113], v[194:195]
	v_mul_f32_e32 v114, v125, v125
	v_mul_f32_e32 v115, v127, v127
	v_cvt_pk_bf16_f32 v112, v124, v125
	v_cvt_pk_bf16_f32 v113, v126, v127
	v_mul_f32_e32 v125, v117, v117
	v_mul_f32_e32 v127, v119, v119
	v_pk_add_f32 v[122:123], v[122:123], v[188:189]
	v_mul_f32_e32 v182, v121, v121
	v_mul_f32_e32 v185, v181, v181
	v_fmac_f32_e32 v114, v124, v124
	v_fmac_f32_e32 v115, v126, v126
	v_fmac_f32_e32 v125, v116, v116
	v_fmac_f32_e32 v127, v118, v118
	v_mul_f32_e32 v183, v123, v123
	v_mul_f32_e32 v186, v179, v179
	v_fmac_f32_e32 v182, v120, v120
	v_fmac_f32_e32 v185, v180, v180
	v_add_f32_e32 v114, v114, v115
	v_add_f32_e32 v115, v125, v127
	v_fmac_f32_e32 v183, v122, v122
	v_fmac_f32_e32 v186, v178, v178
	v_add_f32_e32 v114, v114, v182
	v_add_f32_e32 v115, v115, v185
	v_add_f32_e32 v114, v183, v114
	v_add_f32_e32 v115, v186, v115
	v_add_f32_e32 v124, v114, v115
	ds_bpermute_b32 v125, v176, v124
	v_cvt_pk_bf16_f32 v114, v120, v121
	v_cvt_pk_bf16_f32 v115, v122, v123
	global_store_dwordx4 v[166:167], v[112:115], off
	s_waitcnt lgkmcnt(0)
	s_nop 0
	v_add_f32_e32 v112, v124, v125
	ds_bpermute_b32 v113, v177, v112
	v_cvt_pk_bf16_f32 v114, v116, v117
	v_cvt_pk_bf16_f32 v115, v118, v119
	v_cvt_pk_bf16_f32 v116, v180, v181
	v_cvt_pk_bf16_f32 v117, v178, v179
	global_store_dwordx4 v[166:167], v[114:117], off offset:256
	s_and_saveexec_b64 s[34:35], s[8:9]
	s_cbranch_execz .LBB0_517
	v_lshl_add_u64 v[114:115], v[162:163], 2, s[20:21]
	s_waitcnt lgkmcnt(0)
	v_add_f32_e32 v112, v112, v113
	global_atomic_add_f32 v[114:115], v112, off

.LBB0_604:
	ds_read_b128 v[16:19], v176
	ds_read_b128 v[20:23], v176 offset:1024
	ds_read_b128 v[32:35], v176 offset:2048
	ds_read_b128 v[36:39], v176 offset:3072
	s_add_u32 s41, s10, 0xfff00080
	s_addc_u32 s46, s11, -1
	s_cmp_eq_u32 s39, 60
	s_cselect_b32 s49, s4, s46
	s_cselect_b32 s48, s5, s41
	s_cselect_b32 s47, s6, s15
	s_cselect_b32 s46, s7, s13
	v_lshl_add_u64 v[160:161], s[10:11], 0, v[152:153]
	s_add_i32 m0, s52, 0xc000
	ds_read_b128 v[164:167], v177
	ds_read_b128 v[168:171], v177 offset:1024
	ds_read_b128 v[190:193], v177 offset:2048
	ds_read_b128 v[194:197], v177 offset:3072
	ds_read_b128 v[198:201], v177 offset:4096
	ds_read_b128 v[202:205], v177 offset:5120
	ds_read_b128 v[206:209], v177 offset:6144
	ds_read_b128 v[210:213], v177 offset:7168
	global_load_lds_dwordx4 v[160:161], off
	v_lshl_add_u64 v[160:161], s[10:11], 0, v[154:155]
	s_add_i32 m0, s52, 0xe000
	s_nop 0
	global_load_lds_dwordx4 v[160:161], off
	s_waitcnt lgkmcnt(8)
	s_barrier
	s_waitcnt lgkmcnt(0)
	s_waitcnt lgkmcnt(0)
	v_mfma_f32_16x16x32_bf16 v[140:143], v[16:19], v[164:167], v[140:143]
	v_mfma_f32_16x16x32_bf16 v[140:143], v[20:23], v[168:171], v[140:143]
	v_mfma_f32_16x16x32_bf16 v[136:139], v[32:35], v[164:167], v[136:139]
	v_mfma_f32_16x16x32_bf16 v[136:139], v[36:39], v[168:171], v[136:139]
	v_mfma_f32_16x16x32_bf16 v[124:127], v[16:19], v[190:193], v[124:127]
	v_mfma_f32_16x16x32_bf16 v[124:127], v[20:23], v[194:197], v[124:127]
	v_mfma_f32_16x16x32_bf16 v[120:123], v[32:35], v[190:193], v[120:123]
	v_mfma_f32_16x16x32_bf16 v[120:123], v[36:39], v[194:197], v[120:123]
	v_mfma_f32_16x16x32_bf16 v[108:111], v[16:19], v[198:201], v[108:111]
	v_mfma_f32_16x16x32_bf16 v[108:111], v[20:23], v[202:205], v[108:111]
	v_mfma_f32_16x16x32_bf16 v[104:107], v[32:35], v[198:201], v[104:107]
	v_mfma_f32_16x16x32_bf16 v[104:107], v[36:39], v[202:205], v[104:107]
	v_mfma_f32_16x16x32_bf16 v[92:95], v[16:19], v[206:209], v[92:95]
	v_mfma_f32_16x16x32_bf16 v[92:95], v[20:23], v[210:213], v[92:95]
	v_mfma_f32_16x16x32_bf16 v[88:91], v[32:35], v[206:209], v[88:91]
	v_mfma_f32_16x16x32_bf16 v[88:91], v[36:39], v[210:213], v[88:91]
	s_barrier
	s_add_i32 s41, s81, s51
	v_lshl_add_u64 v[160:161], s[46:47], 0, v[146:147]
	s_mov_b32 m0, s41
	ds_read_b128 v[214:217], v178
	ds_read_b128 v[218:221], v178 offset:1024
	ds_read_b128 v[222:225], v178 offset:2048
	ds_read_b128 v[226:229], v178 offset:3072
	global_load_lds_dwordx4 v[160:161], off
	v_lshl_add_u64 v[230:231], s[46:47], 0, v[150:151]
	s_add_i32 m0, s41, 0x2000
	s_nop 0
	global_load_lds_dwordx4 v[230:231], off
	s_barrier
	s_waitcnt lgkmcnt(0)
	s_waitcnt lgkmcnt(0)
	v_mfma_f32_16x16x32_bf16 v[132:135], v[214:217], v[164:167], v[132:135]
	v_mfma_f32_16x16x32_bf16 v[132:135], v[218:221], v[168:171], v[132:135]
	v_mfma_f32_16x16x32_bf16 v[128:131], v[222:225], v[164:167], v[128:131]
	v_mfma_f32_16x16x32_bf16 v[128:131], v[226:229], v[168:171], v[128:131]
	v_mfma_f32_16x16x32_bf16 v[116:119], v[214:217], v[190:193], v[116:119]
	v_mfma_f32_16x16x32_bf16 v[116:119], v[218:221], v[194:197], v[116:119]
	v_mfma_f32_16x16x32_bf16 v[112:115], v[222:225], v[190:193], v[112:115]
	v_mfma_f32_16x16x32_bf16 v[112:115], v[226:229], v[194:197], v[112:115]
	v_mfma_f32_16x16x32_bf16 v[100:103], v[214:217], v[198:201], v[100:103]
	v_mfma_f32_16x16x32_bf16 v[100:103], v[218:221], v[202:205], v[100:103]
	v_mfma_f32_16x16x32_bf16 v[96:99], v[222:225], v[198:201], v[96:99]
	v_mfma_f32_16x16x32_bf16 v[96:99], v[226:229], v[202:205], v[96:99]
	v_mfma_f32_16x16x32_bf16 v[84:87], v[214:217], v[206:209], v[84:87]
	v_mfma_f32_16x16x32_bf16 v[84:87], v[218:221], v[210:213], v[84:87]
	v_mfma_f32_16x16x32_bf16 v[80:83], v[222:225], v[206:209], v[80:83]
	v_mfma_f32_16x16x32_bf16 v[80:83], v[226:229], v[210:213], v[80:83]
	s_mov_b32 m0, s52
	v_lshl_add_u64 v[232:233], s[48:49], 0, v[144:145]
	s_barrier
	ds_read_b128 v[164:167], v177 offset:16384
	ds_read_b128 v[168:171], v177 offset:17408
	ds_read_b128 v[190:193], v177 offset:18432
	ds_read_b128 v[194:197], v177 offset:19456
	ds_read_b128 v[198:201], v177 offset:20480
	ds_read_b128 v[202:205], v177 offset:21504
	ds_read_b128 v[206:209], v177 offset:22528
	ds_read_b128 v[210:213], v177 offset:23552
	global_load_lds_dwordx4 v[232:233], off
	v_lshl_add_u64 v[234:235], s[48:49], 0, v[148:149]
	s_mov_b32 m0, s53
	s_nop 0
	global_load_lds_dwordx4 v[234:235], off
	s_barrier
	s_waitcnt lgkmcnt(0)
	s_waitcnt lgkmcnt(0)
	v_mfma_f32_16x16x32_bf16 v[76:79], v[16:19], v[164:167], v[76:79]
	v_mfma_f32_16x16x32_bf16 v[76:79], v[20:23], v[168:171], v[76:79]
	v_mfma_f32_16x16x32_bf16 v[72:75], v[32:35], v[164:167], v[72:75]
	v_mfma_f32_16x16x32_bf16 v[72:75], v[36:39], v[168:171], v[72:75]
	v_mfma_f32_16x16x32_bf16 v[60:63], v[16:19], v[190:193], v[60:63]
	v_mfma_f32_16x16x32_bf16 v[60:63], v[20:23], v[194:197], v[60:63]
	v_mfma_f32_16x16x32_bf16 v[56:59], v[32:35], v[190:193], v[56:59]
	v_mfma_f32_16x16x32_bf16 v[56:59], v[36:39], v[194:197], v[56:59]
	v_mfma_f32_16x16x32_bf16 v[44:47], v[16:19], v[198:201], v[44:47]
	v_mfma_f32_16x16x32_bf16 v[44:47], v[20:23], v[202:205], v[44:47]
	v_mfma_f32_16x16x32_bf16 v[40:43], v[32:35], v[198:201], v[40:43]
	v_mfma_f32_16x16x32_bf16 v[40:43], v[36:39], v[202:205], v[40:43]
	v_mfma_f32_16x16x32_bf16 v[12:15], v[16:19], v[206:209], v[12:15]
	v_mfma_f32_16x16x32_bf16 v[12:15], v[20:23], v[210:213], v[12:15]
	v_mfma_f32_16x16x32_bf16 v[8:11], v[32:35], v[206:209], v[8:11]
	v_mfma_f32_16x16x32_bf16 v[8:11], v[36:39], v[210:213], v[8:11]
	s_barrier
	s_add_u32 s54, s46, 0x100000
	s_addc_u32 s55, s47, 0
	s_add_i32 s41, s82, s51
	v_lshl_add_u64 v[16:17], s[54:55], 0, v[146:147]
	s_mov_b32 m0, s41
	s_nop 0
	global_load_lds_dwordx4 v[16:17], off
	v_lshl_add_u64 v[16:17], s[54:55], 0, v[150:151]
	s_add_i32 m0, s41, 0x2000
	s_nop 0
	global_load_lds_dwordx4 v[16:17], off
	s_waitcnt vmcnt(6)
	s_barrier
	v_mfma_f32_16x16x32_bf16 v[28:31], v[214:217], v[198:201], v[28:31]
	v_mfma_f32_16x16x32_bf16 v[28:31], v[218:221], v[202:205], v[28:31]
	v_mfma_f32_16x16x32_bf16 v[24:27], v[222:225], v[198:201], v[24:27]
	v_mfma_f32_16x16x32_bf16 v[24:27], v[226:229], v[202:205], v[24:27]
	v_mfma_f32_16x16x32_bf16 v[4:7], v[214:217], v[206:209], v[4:7]
	v_mfma_f32_16x16x32_bf16 v[4:7], v[218:221], v[210:213], v[4:7]
	v_mfma_f32_16x16x32_bf16 v[0:3], v[222:225], v[206:209], v[0:3]
	v_mfma_f32_16x16x32_bf16 v[0:3], v[226:229], v[210:213], v[0:3]
	v_mfma_f32_16x16x32_bf16 v[16:19], v[214:217], v[164:167], v[68:71]
	v_mfma_f32_16x16x32_bf16 v[16:19], v[218:221], v[168:171], v[16:19]
	v_mfma_f32_16x16x32_bf16 v[20:23], v[222:225], v[164:167], v[64:67]
	v_mfma_f32_16x16x32_bf16 v[20:23], v[226:229], v[168:171], v[20:23]
	v_mfma_f32_16x16x32_bf16 v[32:35], v[214:217], v[190:193], v[52:55]
	v_mfma_f32_16x16x32_bf16 v[32:35], v[218:221], v[194:197], v[32:35]
	v_mfma_f32_16x16x32_bf16 v[36:39], v[222:225], v[190:193], v[48:51]
	v_mfma_f32_16x16x32_bf16 v[36:39], v[226:229], v[194:197], v[36:39]
	s_add_i32 s41, 0, 0x18000
	v_add_u32_e32 v68, s41, v174
	s_barrier
	ds_read_b128 v[48:51], v68
	ds_read_b128 v[52:55], v68 offset:1024
	ds_read_b128 v[64:67], v68 offset:2048
	ds_read_b128 v[68:71], v68 offset:3072
	s_add_u32 s48, s48, 0x100000
	s_addc_u32 s49, s49, 0
	s_mov_b32 m0, s61
	v_lshl_add_u64 v[214:215], s[48:49], 0, v[144:145]
	ds_read_b128 v[164:167], v177 offset:32768
	ds_read_b128 v[168:171], v177 offset:33792
	ds_read_b128 v[190:193], v177 offset:34816
	ds_read_b128 v[194:197], v177 offset:35840
	ds_read_b128 v[198:201], v177 offset:36864
	ds_read_b128 v[202:205], v177 offset:37888
	ds_read_b128 v[206:209], v177 offset:38912
	ds_read_b128 v[210:213], v177 offset:39936
	global_load_lds_dwordx4 v[214:215], off
	v_lshl_add_u64 v[214:215], s[48:49], 0, v[148:149]
	s_mov_b32 m0, s74
	s_nop 0
	global_load_lds_dwordx4 v[214:215], off
	s_waitcnt lgkmcnt(8)
	s_barrier
	s_waitcnt lgkmcnt(0)
	s_waitcnt lgkmcnt(0)
	v_mfma_f32_16x16x32_bf16 v[140:143], v[48:51], v[164:167], v[140:143]
	v_mfma_f32_16x16x32_bf16 v[140:143], v[52:55], v[168:171], v[140:143]
	v_mfma_f32_16x16x32_bf16 v[136:139], v[64:67], v[164:167], v[136:139]
	v_mfma_f32_16x16x32_bf16 v[136:139], v[68:71], v[168:171], v[136:139]
	v_mfma_f32_16x16x32_bf16 v[124:127], v[48:51], v[190:193], v[124:127]
	v_mfma_f32_16x16x32_bf16 v[124:127], v[52:55], v[194:197], v[124:127]
	v_mfma_f32_16x16x32_bf16 v[120:123], v[64:67], v[190:193], v[120:123]
	v_mfma_f32_16x16x32_bf16 v[120:123], v[68:71], v[194:197], v[120:123]
	v_mfma_f32_16x16x32_bf16 v[108:111], v[48:51], v[198:201], v[108:111]
	v_mfma_f32_16x16x32_bf16 v[108:111], v[52:55], v[202:205], v[108:111]
	v_mfma_f32_16x16x32_bf16 v[104:107], v[64:67], v[198:201], v[104:107]
	v_mfma_f32_16x16x32_bf16 v[104:107], v[68:71], v[202:205], v[104:107]
	v_mfma_f32_16x16x32_bf16 v[92:95], v[48:51], v[206:209], v[92:95]
	v_mfma_f32_16x16x32_bf16 v[92:95], v[52:55], v[210:213], v[92:95]
	v_mfma_f32_16x16x32_bf16 v[88:91], v[64:67], v[206:209], v[88:91]
	v_mfma_f32_16x16x32_bf16 v[88:91], v[68:71], v[210:213], v[88:91]
	s_barrier
	s_add_i32 s48, 0, 0x1c000
	s_add_i32 s41, s41, s51
	v_add_u32_e32 v163, s48, v174
	v_lshl_add_u64 v[160:161], v[160:161], 0, s[22:23]
	s_mov_b32 m0, s41
	ds_read_b128 v[214:217], v163
	ds_read_b128 v[218:221], v163 offset:1024
	ds_read_b128 v[222:225], v163 offset:2048
	ds_read_b128 v[226:229], v163 offset:3072
	global_load_lds_dwordx4 v[160:161], off
	v_lshl_add_u64 v[160:161], v[230:231], 0, s[22:23]
	s_add_i32 m0, s41, 0x2000
	s_nop 0
	global_load_lds_dwordx4 v[160:161], off
	s_barrier
	s_waitcnt lgkmcnt(0)
	s_waitcnt lgkmcnt(0)
	v_mfma_f32_16x16x32_bf16 v[132:135], v[214:217], v[164:167], v[132:135]
	v_mfma_f32_16x16x32_bf16 v[132:135], v[218:221], v[168:171], v[132:135]
	v_mfma_f32_16x16x32_bf16 v[128:131], v[222:225], v[164:167], v[128:131]
	v_mfma_f32_16x16x32_bf16 v[128:131], v[226:229], v[168:171], v[128:131]
	v_mfma_f32_16x16x32_bf16 v[116:119], v[214:217], v[190:193], v[116:119]
	v_mfma_f32_16x16x32_bf16 v[116:119], v[218:221], v[194:197], v[116:119]
	v_mfma_f32_16x16x32_bf16 v[112:115], v[222:225], v[190:193], v[112:115]
	v_mfma_f32_16x16x32_bf16 v[112:115], v[226:229], v[194:197], v[112:115]
	v_mfma_f32_16x16x32_bf16 v[100:103], v[214:217], v[198:201], v[100:103]
	v_mfma_f32_16x16x32_bf16 v[100:103], v[218:221], v[202:205], v[100:103]
	v_mfma_f32_16x16x32_bf16 v[96:99], v[222:225], v[198:201], v[96:99]
	v_mfma_f32_16x16x32_bf16 v[96:99], v[226:229], v[202:205], v[96:99]
	v_mfma_f32_16x16x32_bf16 v[84:87], v[214:217], v[206:209], v[84:87]
	v_mfma_f32_16x16x32_bf16 v[84:87], v[218:221], v[210:213], v[84:87]
	v_mfma_f32_16x16x32_bf16 v[80:83], v[222:225], v[206:209], v[80:83]
	v_mfma_f32_16x16x32_bf16 v[80:83], v[226:229], v[210:213], v[80:83]
	s_mov_b32 m0, s76
	v_lshl_add_u64 v[160:161], v[232:233], 0, s[22:23]
	s_barrier
	ds_read_b128 v[164:167], v177 offset:49152
	ds_read_b128 v[168:171], v177 offset:50176
	ds_read_b128 v[190:193], v177 offset:51200
	ds_read_b128 v[194:197], v177 offset:52224
	ds_read_b128 v[198:201], v177 offset:53248
	ds_read_b128 v[202:205], v177 offset:54272
	ds_read_b128 v[206:209], v177 offset:55296
	ds_read_b128 v[210:213], v177 offset:56320
	global_load_lds_dwordx4 v[160:161], off
	v_lshl_add_u64 v[160:161], v[234:235], 0, s[22:23]
	s_mov_b32 m0, s77
	s_nop 0
	global_load_lds_dwordx4 v[160:161], off
	s_barrier
	s_waitcnt lgkmcnt(0)
	s_waitcnt lgkmcnt(0)
	v_mfma_f32_16x16x32_bf16 v[76:79], v[48:51], v[164:167], v[76:79]
	v_mfma_f32_16x16x32_bf16 v[76:79], v[52:55], v[168:171], v[76:79]
	v_mfma_f32_16x16x32_bf16 v[72:75], v[64:67], v[164:167], v[72:75]
	v_mfma_f32_16x16x32_bf16 v[72:75], v[68:71], v[168:171], v[72:75]
	v_mfma_f32_16x16x32_bf16 v[60:63], v[48:51], v[190:193], v[60:63]
	v_mfma_f32_16x16x32_bf16 v[60:63], v[52:55], v[194:197], v[60:63]
	v_mfma_f32_16x16x32_bf16 v[56:59], v[64:67], v[190:193], v[56:59]
	v_mfma_f32_16x16x32_bf16 v[56:59], v[68:71], v[194:197], v[56:59]
	v_mfma_f32_16x16x32_bf16 v[44:47], v[48:51], v[198:201], v[44:47]
	v_mfma_f32_16x16x32_bf16 v[44:47], v[52:55], v[202:205], v[44:47]
	v_mfma_f32_16x16x32_bf16 v[40:43], v[64:67], v[198:201], v[40:43]
	v_mfma_f32_16x16x32_bf16 v[40:43], v[68:71], v[202:205], v[40:43]
	v_mfma_f32_16x16x32_bf16 v[12:15], v[48:51], v[206:209], v[12:15]
	v_mfma_f32_16x16x32_bf16 v[12:15], v[52:55], v[210:213], v[12:15]
	v_mfma_f32_16x16x32_bf16 v[8:11], v[64:67], v[206:209], v[8:11]
	v_mfma_f32_16x16x32_bf16 v[8:11], v[68:71], v[210:213], v[8:11]
	s_barrier
	s_add_u32 s46, s46, 0x100080
	s_addc_u32 s47, s47, 0
	s_add_i32 s41, s48, s51
	v_lshl_add_u64 v[48:49], s[46:47], 0, v[146:147]
	s_mov_b32 m0, s41
	s_nop 0
	global_load_lds_dwordx4 v[48:49], off
	v_lshl_add_u64 v[48:49], s[46:47], 0, v[150:151]
	s_add_i32 m0, s41, 0x2000
	s_nop 0
	global_load_lds_dwordx4 v[48:49], off
	s_waitcnt vmcnt(6)
	s_barrier
	v_mfma_f32_16x16x32_bf16 v[16:19], v[214:217], v[164:167], v[16:19]
	v_mfma_f32_16x16x32_bf16 v[68:71], v[218:221], v[168:171], v[16:19]
	v_mfma_f32_16x16x32_bf16 v[16:19], v[222:225], v[164:167], v[20:23]
	v_mfma_f32_16x16x32_bf16 v[64:67], v[226:229], v[168:171], v[16:19]
	v_mfma_f32_16x16x32_bf16 v[16:19], v[214:217], v[190:193], v[32:35]
	v_mfma_f32_16x16x32_bf16 v[52:55], v[218:221], v[194:197], v[16:19]
	v_mfma_f32_16x16x32_bf16 v[16:19], v[222:225], v[190:193], v[36:39]
	v_mfma_f32_16x16x32_bf16 v[48:51], v[226:229], v[194:197], v[16:19]
	v_mfma_f32_16x16x32_bf16 v[16:19], v[214:217], v[198:201], v[28:31]
	v_mfma_f32_16x16x32_bf16 v[28:31], v[218:221], v[202:205], v[16:19]
	v_mfma_f32_16x16x32_bf16 v[16:19], v[222:225], v[198:201], v[24:27]
	v_mfma_f32_16x16x32_bf16 v[24:27], v[226:229], v[202:205], v[16:19]
	v_mfma_f32_16x16x32_bf16 v[4:7], v[214:217], v[206:209], v[4:7]
	v_mfma_f32_16x16x32_bf16 v[4:7], v[218:221], v[210:213], v[4:7]
	v_mfma_f32_16x16x32_bf16 v[0:3], v[222:225], v[206:209], v[0:3]
	v_mfma_f32_16x16x32_bf16 v[0:3], v[226:229], v[210:213], v[0:3]
	s_add_i32 s39, s39, 2
	s_add_u32 s10, s10, 0x100
	s_addc_u32 s11, s11, 0
	s_add_u32 s13, s13, 0x100
	s_addc_u32 s15, s15, 0
	s_cmp_gt_u32 s39, 61
	s_barrier
	s_cbranch_scc0 .LBB0_604
	s_ashr_i32 s4, s12, 4
	s_cmp_eq_u32 s4, 1
	v_lshl_or_b32 v160, s12, 8, v175
	v_mov_b32_e32 v36, 0
	s_cselect_b64 s[46:47], -1, 0
	s_cmp_lg_u32 s4, 1
	v_mov_b32_e32 v37, 0
	v_mov_b32_e32 v38, 0
	v_mov_b32_e32 v39, 0
	v_mov_b32_e32 v32, 0
	v_mov_b32_e32 v33, 0
	v_mov_b32_e32 v34, 0
	v_mov_b32_e32 v35, 0
	v_mov_b32_e32 v20, 0
	v_mov_b32_e32 v21, 0
	v_mov_b32_e32 v22, 0
	v_mov_b32_e32 v23, 0
	v_mov_b32_e32 v16, 0
	v_mov_b32_e32 v17, 0
	v_mov_b32_e32 v18, 0
	v_mov_b32_e32 v19, 0
	s_cbranch_scc1 .LBB0_607
	v_mov_b32_e32 v161, v147
	v_lshl_add_u64 v[16:17], v[160:161], 2, s[18:19]
	v_add_co_u32_e32 v20, vcc, 0xffffc000, v16
	v_lshl_add_u64 v[18:19], v[16:17], 0, s[24:25]
	s_nop 0
	v_addc_co_u32_e32 v21, vcc, -1, v17, vcc
	global_load_dwordx4 v[36:39], v[20:21], off
	global_load_dwordx4 v[32:35], v[18:19], off offset:16
	v_lshl_add_u64 v[18:19], v[16:17], 0, s[26:27]
	v_add_co_u32_e32 v16, vcc, 0xffffd000, v16
	s_nop 1
	v_addc_co_u32_e32 v17, vcc, -1, v17, vcc
	global_load_dwordx4 v[20:23], v[16:17], off offset:-3584
	s_nop 0
	global_load_dwordx4 v[16:19], v[18:19], off offset:16

.LBB0_981:
	ds_read_b128 v[128:131], v163
	ds_read_b128 v[132:135], v163 offset:1024
	ds_read_b128 v[152:155], v163 offset:2048
	ds_read_b128 v[156:159], v163 offset:3072
	s_add_u32 s26, s24, 0xffc00080
	s_addc_u32 s27, s25, -1
	s_cmp_eq_u32 s47, 60
	s_cselect_b32 s29, s15, s27
	s_cselect_b32 s28, s21, s26
	s_cselect_b32 s27, s13, s46
	s_cselect_b32 s26, s44, s45
	v_lshl_add_u64 v[182:183], s[24:25], 0, v[144:145]
	s_add_i32 m0, s23, 0xc000
	ds_read_b128 v[168:171], v164
	ds_read_b128 v[174:177], v164 offset:1024
	ds_read_b128 v[178:181], v164 offset:2048
	ds_read_b128 v[186:189], v164 offset:3072
	ds_read_b128 v[190:193], v164 offset:4096
	ds_read_b128 v[194:197], v164 offset:5120
	ds_read_b128 v[198:201], v164 offset:6144
	ds_read_b128 v[202:205], v164 offset:7168
	global_load_lds_dwordx4 v[182:183], off
	v_lshl_add_u64 v[182:183], s[24:25], 0, v[146:147]
	s_add_i32 m0, s23, 0xe000
	s_nop 0
	global_load_lds_dwordx4 v[182:183], off
	s_waitcnt lgkmcnt(8)
	s_barrier
	s_waitcnt lgkmcnt(0)
	s_waitcnt lgkmcnt(0)
	v_mfma_f32_16x16x32_bf16 v[124:127], v[128:131], v[168:171], v[124:127]
	v_mfma_f32_16x16x32_bf16 v[124:127], v[132:135], v[174:177], v[124:127]
	v_mfma_f32_16x16x32_bf16 v[120:123], v[152:155], v[168:171], v[120:123]
	v_mfma_f32_16x16x32_bf16 v[120:123], v[156:159], v[174:177], v[120:123]
	v_mfma_f32_16x16x32_bf16 v[108:111], v[128:131], v[178:181], v[108:111]
	v_mfma_f32_16x16x32_bf16 v[108:111], v[132:135], v[186:189], v[108:111]
	v_mfma_f32_16x16x32_bf16 v[104:107], v[152:155], v[178:181], v[104:107]
	v_mfma_f32_16x16x32_bf16 v[104:107], v[156:159], v[186:189], v[104:107]
	v_mfma_f32_16x16x32_bf16 v[92:95], v[128:131], v[190:193], v[92:95]
	v_mfma_f32_16x16x32_bf16 v[92:95], v[132:135], v[194:197], v[92:95]
	v_mfma_f32_16x16x32_bf16 v[88:91], v[152:155], v[190:193], v[88:91]
	v_mfma_f32_16x16x32_bf16 v[88:91], v[156:159], v[194:197], v[88:91]
	v_mfma_f32_16x16x32_bf16 v[76:79], v[128:131], v[198:201], v[76:79]
	v_mfma_f32_16x16x32_bf16 v[76:79], v[132:135], v[202:205], v[76:79]
	v_mfma_f32_16x16x32_bf16 v[72:75], v[152:155], v[198:201], v[72:75]
	v_mfma_f32_16x16x32_bf16 v[72:75], v[156:159], v[202:205], v[72:75]
	s_barrier
	s_add_i32 s48, s42, s30
	v_lshl_add_u64 v[182:183], s[26:27], 0, v[138:139]
	s_mov_b32 m0, s48
	ds_read_b128 v[206:209], v165
	ds_read_b128 v[210:213], v165 offset:1024
	ds_read_b128 v[214:217], v165 offset:2048
	ds_read_b128 v[218:221], v165 offset:3072
	global_load_lds_dwordx4 v[182:183], off
	v_lshl_add_u64 v[222:223], s[26:27], 0, v[142:143]
	s_add_i32 m0, s48, 0x2000
	s_nop 0
	global_load_lds_dwordx4 v[222:223], off
	s_barrier
	s_waitcnt lgkmcnt(0)
	s_waitcnt lgkmcnt(0)
	v_mfma_f32_16x16x32_bf16 v[116:119], v[206:209], v[168:171], v[116:119]
	v_mfma_f32_16x16x32_bf16 v[116:119], v[210:213], v[174:177], v[116:119]
	v_mfma_f32_16x16x32_bf16 v[112:115], v[214:217], v[168:171], v[112:115]
	v_mfma_f32_16x16x32_bf16 v[112:115], v[218:221], v[174:177], v[112:115]
	v_mfma_f32_16x16x32_bf16 v[100:103], v[206:209], v[178:181], v[100:103]
	v_mfma_f32_16x16x32_bf16 v[100:103], v[210:213], v[186:189], v[100:103]
	v_mfma_f32_16x16x32_bf16 v[96:99], v[214:217], v[178:181], v[96:99]
	v_mfma_f32_16x16x32_bf16 v[96:99], v[218:221], v[186:189], v[96:99]
	v_mfma_f32_16x16x32_bf16 v[84:87], v[206:209], v[190:193], v[84:87]
	v_mfma_f32_16x16x32_bf16 v[84:87], v[210:213], v[194:197], v[84:87]
	v_mfma_f32_16x16x32_bf16 v[80:83], v[214:217], v[190:193], v[80:83]
	v_mfma_f32_16x16x32_bf16 v[80:83], v[218:221], v[194:197], v[80:83]
	v_mfma_f32_16x16x32_bf16 v[68:71], v[206:209], v[198:201], v[68:71]
	v_mfma_f32_16x16x32_bf16 v[68:71], v[210:213], v[202:205], v[68:71]
	v_mfma_f32_16x16x32_bf16 v[64:67], v[214:217], v[198:201], v[64:67]
	v_mfma_f32_16x16x32_bf16 v[64:67], v[218:221], v[202:205], v[64:67]
	s_mov_b32 m0, s23
	v_lshl_add_u64 v[224:225], s[28:29], 0, v[136:137]
	s_barrier
	ds_read_b128 v[168:171], v164 offset:16384
	ds_read_b128 v[174:177], v164 offset:17408
	ds_read_b128 v[178:181], v164 offset:18432
	ds_read_b128 v[186:189], v164 offset:19456
	ds_read_b128 v[190:193], v164 offset:20480
	ds_read_b128 v[194:197], v164 offset:21504
	ds_read_b128 v[198:201], v164 offset:22528
	ds_read_b128 v[202:205], v164 offset:23552
	global_load_lds_dwordx4 v[224:225], off
	v_lshl_add_u64 v[226:227], s[28:29], 0, v[140:141]
	s_mov_b32 m0, s31
	s_nop 0
	global_load_lds_dwordx4 v[226:227], off
	s_barrier
	s_waitcnt lgkmcnt(0)
	s_waitcnt lgkmcnt(0)
	v_mfma_f32_16x16x32_bf16 v[60:63], v[128:131], v[168:171], v[60:63]
	v_mfma_f32_16x16x32_bf16 v[60:63], v[132:135], v[174:177], v[60:63]
	v_mfma_f32_16x16x32_bf16 v[56:59], v[152:155], v[168:171], v[56:59]
	v_mfma_f32_16x16x32_bf16 v[56:59], v[156:159], v[174:177], v[56:59]
	v_mfma_f32_16x16x32_bf16 v[44:47], v[128:131], v[178:181], v[44:47]
	v_mfma_f32_16x16x32_bf16 v[44:47], v[132:135], v[186:189], v[44:47]
	v_mfma_f32_16x16x32_bf16 v[40:43], v[152:155], v[178:181], v[40:43]
	v_mfma_f32_16x16x32_bf16 v[40:43], v[156:159], v[186:189], v[40:43]
	v_mfma_f32_16x16x32_bf16 v[28:31], v[128:131], v[190:193], v[28:31]
	v_mfma_f32_16x16x32_bf16 v[28:31], v[132:135], v[194:197], v[28:31]
	v_mfma_f32_16x16x32_bf16 v[24:27], v[152:155], v[190:193], v[24:27]
	v_mfma_f32_16x16x32_bf16 v[24:27], v[156:159], v[194:197], v[24:27]
	v_mfma_f32_16x16x32_bf16 v[12:15], v[128:131], v[198:201], v[12:15]
	v_mfma_f32_16x16x32_bf16 v[12:15], v[132:135], v[202:205], v[12:15]
	v_mfma_f32_16x16x32_bf16 v[8:11], v[152:155], v[198:201], v[8:11]
	v_mfma_f32_16x16x32_bf16 v[8:11], v[156:159], v[202:205], v[8:11]
	s_barrier
	s_add_u32 s48, s26, 0x100000
	s_addc_u32 s49, s27, 0
	s_add_i32 s50, s43, s30
	v_lshl_add_u64 v[128:129], s[48:49], 0, v[138:139]
	s_mov_b32 m0, s50
	s_nop 0
	global_load_lds_dwordx4 v[128:129], off
	v_lshl_add_u64 v[128:129], s[48:49], 0, v[142:143]
	s_add_i32 m0, s50, 0x2000
	s_nop 0
	global_load_lds_dwordx4 v[128:129], off
	s_waitcnt vmcnt(6)
	s_barrier
	v_mfma_f32_16x16x32_bf16 v[52:55], v[206:209], v[168:171], v[52:55]
	v_mfma_f32_16x16x32_bf16 v[52:55], v[210:213], v[174:177], v[52:55]
	v_mfma_f32_16x16x32_bf16 v[48:51], v[214:217], v[168:171], v[48:51]
	v_mfma_f32_16x16x32_bf16 v[48:51], v[218:221], v[174:177], v[48:51]
	v_mfma_f32_16x16x32_bf16 v[36:39], v[206:209], v[178:181], v[36:39]
	v_mfma_f32_16x16x32_bf16 v[36:39], v[210:213], v[186:189], v[36:39]
	v_mfma_f32_16x16x32_bf16 v[32:35], v[214:217], v[178:181], v[32:35]
	v_mfma_f32_16x16x32_bf16 v[32:35], v[218:221], v[186:189], v[32:35]
	v_mfma_f32_16x16x32_bf16 v[20:23], v[206:209], v[190:193], v[20:23]
	v_mfma_f32_16x16x32_bf16 v[20:23], v[210:213], v[194:197], v[20:23]
	v_mfma_f32_16x16x32_bf16 v[16:19], v[214:217], v[190:193], v[16:19]
	v_mfma_f32_16x16x32_bf16 v[16:19], v[218:221], v[194:197], v[16:19]
	v_mfma_f32_16x16x32_bf16 v[4:7], v[206:209], v[198:201], v[4:7]
	v_mfma_f32_16x16x32_bf16 v[4:7], v[210:213], v[202:205], v[4:7]
	v_mfma_f32_16x16x32_bf16 v[0:3], v[214:217], v[198:201], v[0:3]
	v_mfma_f32_16x16x32_bf16 v[0:3], v[218:221], v[202:205], v[0:3]
	s_add_i32 s48, 0, 0x18000
	v_add_u32_e32 v156, s48, v161
	s_barrier
	ds_read_b128 v[128:131], v156
	ds_read_b128 v[132:135], v156 offset:1024
	ds_read_b128 v[152:155], v156 offset:2048
	ds_read_b128 v[156:159], v156 offset:3072
	s_add_u32 s28, s28, 0x400000
	s_addc_u32 s29, s29, 0
	s_mov_b32 m0, s34
	v_lshl_add_u64 v[206:207], s[28:29], 0, v[136:137]
	ds_read_b128 v[168:171], v164 offset:32768
	ds_read_b128 v[174:177], v164 offset:33792
	ds_read_b128 v[178:181], v164 offset:34816
	ds_read_b128 v[186:189], v164 offset:35840
	ds_read_b128 v[190:193], v164 offset:36864
	ds_read_b128 v[194:197], v164 offset:37888
	ds_read_b128 v[198:201], v164 offset:38912
	ds_read_b128 v[202:205], v164 offset:39936
	global_load_lds_dwordx4 v[206:207], off
	v_lshl_add_u64 v[206:207], s[28:29], 0, v[140:141]
	s_mov_b32 m0, s35
	s_nop 0
	global_load_lds_dwordx4 v[206:207], off
	s_waitcnt lgkmcnt(8)
	s_barrier
	s_waitcnt lgkmcnt(0)
	s_waitcnt lgkmcnt(0)
	v_mfma_f32_16x16x32_bf16 v[124:127], v[128:131], v[168:171], v[124:127]
	v_mfma_f32_16x16x32_bf16 v[124:127], v[132:135], v[174:177], v[124:127]
	v_mfma_f32_16x16x32_bf16 v[120:123], v[152:155], v[168:171], v[120:123]
	v_mfma_f32_16x16x32_bf16 v[120:123], v[156:159], v[174:177], v[120:123]
	v_mfma_f32_16x16x32_bf16 v[108:111], v[128:131], v[178:181], v[108:111]
	v_mfma_f32_16x16x32_bf16 v[108:111], v[132:135], v[186:189], v[108:111]
	v_mfma_f32_16x16x32_bf16 v[104:107], v[152:155], v[178:181], v[104:107]
	v_mfma_f32_16x16x32_bf16 v[104:107], v[156:159], v[186:189], v[104:107]
	v_mfma_f32_16x16x32_bf16 v[92:95], v[128:131], v[190:193], v[92:95]
	v_mfma_f32_16x16x32_bf16 v[92:95], v[132:135], v[194:197], v[92:95]
	v_mfma_f32_16x16x32_bf16 v[88:91], v[152:155], v[190:193], v[88:91]
	v_mfma_f32_16x16x32_bf16 v[88:91], v[156:159], v[194:197], v[88:91]
	v_mfma_f32_16x16x32_bf16 v[76:79], v[128:131], v[198:201], v[76:79]
	v_mfma_f32_16x16x32_bf16 v[76:79], v[132:135], v[202:205], v[76:79]
	v_mfma_f32_16x16x32_bf16 v[72:75], v[152:155], v[198:201], v[72:75]
	v_mfma_f32_16x16x32_bf16 v[72:75], v[156:159], v[202:205], v[72:75]
	s_barrier
	s_add_i32 s28, 0, 0x1c000
	s_add_i32 s29, s48, s30
	v_add_u32_e32 v167, s28, v161
	v_lshl_add_u64 v[182:183], v[182:183], 0, s[10:11]
	s_mov_b32 m0, s29
	ds_read_b128 v[206:209], v167
	ds_read_b128 v[210:213], v167 offset:1024
	ds_read_b128 v[214:217], v167 offset:2048
	ds_read_b128 v[218:221], v167 offset:3072
	global_load_lds_dwordx4 v[182:183], off
	v_lshl_add_u64 v[182:183], v[222:223], 0, s[10:11]
	s_add_i32 m0, s29, 0x2000
	s_nop 0
	global_load_lds_dwordx4 v[182:183], off
	s_barrier
	s_waitcnt lgkmcnt(0)
	s_waitcnt lgkmcnt(0)
	v_mfma_f32_16x16x32_bf16 v[116:119], v[206:209], v[168:171], v[116:119]
	v_mfma_f32_16x16x32_bf16 v[116:119], v[210:213], v[174:177], v[116:119]
	v_mfma_f32_16x16x32_bf16 v[112:115], v[214:217], v[168:171], v[112:115]
	v_mfma_f32_16x16x32_bf16 v[112:115], v[218:221], v[174:177], v[112:115]
	v_mfma_f32_16x16x32_bf16 v[100:103], v[206:209], v[178:181], v[100:103]
	v_mfma_f32_16x16x32_bf16 v[100:103], v[210:213], v[186:189], v[100:103]
	v_mfma_f32_16x16x32_bf16 v[96:99], v[214:217], v[178:181], v[96:99]
	v_mfma_f32_16x16x32_bf16 v[96:99], v[218:221], v[186:189], v[96:99]
	v_mfma_f32_16x16x32_bf16 v[84:87], v[206:209], v[190:193], v[84:87]
	v_mfma_f32_16x16x32_bf16 v[84:87], v[210:213], v[194:197], v[84:87]
	v_mfma_f32_16x16x32_bf16 v[80:83], v[214:217], v[190:193], v[80:83]
	v_mfma_f32_16x16x32_bf16 v[80:83], v[218:221], v[194:197], v[80:83]
	v_mfma_f32_16x16x32_bf16 v[68:71], v[206:209], v[198:201], v[68:71]
	v_mfma_f32_16x16x32_bf16 v[68:71], v[210:213], v[202:205], v[68:71]
	v_mfma_f32_16x16x32_bf16 v[64:67], v[214:217], v[198:201], v[64:67]
	v_mfma_f32_16x16x32_bf16 v[64:67], v[218:221], v[202:205], v[64:67]
	s_mov_b32 m0, s37
	v_lshl_add_u64 v[182:183], v[224:225], 0, s[10:11]
	s_barrier
	ds_read_b128 v[168:171], v164 offset:49152
	ds_read_b128 v[174:177], v164 offset:50176
	ds_read_b128 v[178:181], v164 offset:51200
	ds_read_b128 v[186:189], v164 offset:52224
	ds_read_b128 v[190:193], v164 offset:53248
	ds_read_b128 v[194:197], v164 offset:54272
	ds_read_b128 v[198:201], v164 offset:55296
	ds_read_b128 v[202:205], v164 offset:56320
	global_load_lds_dwordx4 v[182:183], off
	v_lshl_add_u64 v[182:183], v[226:227], 0, s[10:11]
	s_mov_b32 m0, s38
	s_nop 0
	global_load_lds_dwordx4 v[182:183], off
	s_barrier
	s_waitcnt lgkmcnt(0)
	s_waitcnt lgkmcnt(0)
	v_mfma_f32_16x16x32_bf16 v[60:63], v[128:131], v[168:171], v[60:63]
	v_mfma_f32_16x16x32_bf16 v[60:63], v[132:135], v[174:177], v[60:63]
	v_mfma_f32_16x16x32_bf16 v[56:59], v[152:155], v[168:171], v[56:59]
	v_mfma_f32_16x16x32_bf16 v[56:59], v[156:159], v[174:177], v[56:59]
	v_mfma_f32_16x16x32_bf16 v[44:47], v[128:131], v[178:181], v[44:47]
	v_mfma_f32_16x16x32_bf16 v[44:47], v[132:135], v[186:189], v[44:47]
	v_mfma_f32_16x16x32_bf16 v[40:43], v[152:155], v[178:181], v[40:43]
	v_mfma_f32_16x16x32_bf16 v[40:43], v[156:159], v[186:189], v[40:43]
	v_mfma_f32_16x16x32_bf16 v[28:31], v[128:131], v[190:193], v[28:31]
	v_mfma_f32_16x16x32_bf16 v[28:31], v[132:135], v[194:197], v[28:31]
	v_mfma_f32_16x16x32_bf16 v[24:27], v[152:155], v[190:193], v[24:27]
	v_mfma_f32_16x16x32_bf16 v[24:27], v[156:159], v[194:197], v[24:27]
	v_mfma_f32_16x16x32_bf16 v[12:15], v[128:131], v[198:201], v[12:15]
	v_mfma_f32_16x16x32_bf16 v[12:15], v[132:135], v[202:205], v[12:15]
	v_mfma_f32_16x16x32_bf16 v[8:11], v[152:155], v[198:201], v[8:11]
	v_mfma_f32_16x16x32_bf16 v[8:11], v[156:159], v[202:205], v[8:11]
	s_barrier
	s_add_u32 s26, s26, 0x100080
	s_addc_u32 s27, s27, 0
	s_add_i32 s28, s28, s30
	v_lshl_add_u64 v[128:129], s[26:27], 0, v[138:139]
	s_mov_b32 m0, s28
	s_nop 0
	global_load_lds_dwordx4 v[128:129], off
	v_lshl_add_u64 v[128:129], s[26:27], 0, v[142:143]
	s_add_i32 m0, s28, 0x2000
	s_nop 0
	global_load_lds_dwordx4 v[128:129], off
	s_waitcnt vmcnt(6)
	s_barrier
	v_mfma_f32_16x16x32_bf16 v[52:55], v[206:209], v[168:171], v[52:55]
	v_mfma_f32_16x16x32_bf16 v[52:55], v[210:213], v[174:177], v[52:55]
	v_mfma_f32_16x16x32_bf16 v[48:51], v[214:217], v[168:171], v[48:51]
	v_mfma_f32_16x16x32_bf16 v[48:51], v[218:221], v[174:177], v[48:51]
	v_mfma_f32_16x16x32_bf16 v[36:39], v[206:209], v[178:181], v[36:39]
	v_mfma_f32_16x16x32_bf16 v[36:39], v[210:213], v[186:189], v[36:39]
	v_mfma_f32_16x16x32_bf16 v[32:35], v[214:217], v[178:181], v[32:35]
	v_mfma_f32_16x16x32_bf16 v[32:35], v[218:221], v[186:189], v[32:35]
	v_mfma_f32_16x16x32_bf16 v[20:23], v[206:209], v[190:193], v[20:23]
	v_mfma_f32_16x16x32_bf16 v[20:23], v[210:213], v[194:197], v[20:23]
	v_mfma_f32_16x16x32_bf16 v[16:19], v[214:217], v[190:193], v[16:19]
	v_mfma_f32_16x16x32_bf16 v[16:19], v[218:221], v[194:197], v[16:19]
	v_mfma_f32_16x16x32_bf16 v[4:7], v[206:209], v[198:201], v[4:7]
	v_mfma_f32_16x16x32_bf16 v[4:7], v[210:213], v[202:205], v[4:7]
	v_mfma_f32_16x16x32_bf16 v[0:3], v[214:217], v[198:201], v[0:3]
	v_mfma_f32_16x16x32_bf16 v[0:3], v[218:221], v[202:205], v[0:3]
	s_add_i32 s47, s47, 2
	s_add_u32 s24, s24, 0x100
	s_addc_u32 s25, s25, 0
	s_add_u32 s45, s45, 0x100
	s_addc_u32 s46, s46, 0
	s_cmp_gt_u32 s47, 61
	s_barrier
	s_cbranch_scc0 .LBB0_981
	v_lshl_add_u32 v156, s20, 8, v160
	v_lshl_or_b32 v152, s22, 8, v162
	v_ashrrev_i32_e32 v157, 31, v156
	v_ashrrev_i32_e32 v153, 31, v152
	v_lshlrev_b64 v[128:129], 13, v[156:157]
	v_lshl_add_u64 v[128:129], s[56:57], 0, v[128:129]
	v_lshlrev_b64 v[154:155], 1, v[152:153]
	v_lshl_add_u64 v[128:129], v[128:129], 0, v[154:155]
	global_load_dwordx4 v[168:171], v[128:129], off
	global_load_dwordx4 v[174:177], v[128:129], off offset:256
	v_or_b32_e32 v158, 16, v156
	v_ashrrev_i32_e32 v159, 31, v158
	v_lshlrev_b64 v[128:129], 13, v[158:159]
	v_lshl_add_u64 v[128:129], s[56:57], 0, v[128:129]
	v_lshl_add_u64 v[128:129], v[128:129], 0, v[154:155]
	global_load_dwordx4 v[132:135], v[128:129], off
	s_nop 0
	global_load_dwordx4 v[128:131], v[128:129], off offset:256
	v_and_b32_e32 v173, 64, v166
	v_xor_b32_e32 v167, 16, v166
	v_add_u32_e32 v173, 64, v173
	v_xor_b32_e32 v180, 32, v166
	v_cmp_lt_i32_e32 vcc, v167, v173
	v_lshlrev_b64 v[178:179], 15, v[156:157]
	v_lshl_add_u64 v[178:179], s[68:69], 0, v[178:179]
	v_cndmask_b32_e32 v167, v166, v167, vcc
	v_cmp_lt_i32_e32 vcc, v180, v173
	v_lshlrev_b32_e32 v167, 2, v167
	v_lshl_add_u64 v[178:179], v[178:179], 0, v[154:155]
	v_cndmask_b32_e32 v173, v166, v180, vcc
	s_waitcnt vmcnt(0)
	v_lshlrev_b32_e32 v180, 16, v168
	v_and_b32_e32 v181, 0xffff0000, v168
	v_lshlrev_b32_e32 v168, 16, v169
	v_and_b32_e32 v169, 0xffff0000, v169
	v_lshlrev_b32_e32 v186, 16, v174
	v_and_b32_e32 v187, 0xffff0000, v174
	v_lshlrev_b32_e32 v174, 16, v175
	v_and_b32_e32 v175, 0xffff0000, v175
	v_lshlrev_b32_e32 v182, 16, v170
	v_and_b32_e32 v183, 0xffff0000, v170
	v_lshlrev_b32_e32 v170, 16, v171
	v_and_b32_e32 v171, 0xffff0000, v171
	v_lshlrev_b32_e32 v188, 16, v176
	v_and_b32_e32 v189, 0xffff0000, v176
	v_lshlrev_b32_e32 v176, 16, v177
	v_and_b32_e32 v177, 0xffff0000, v177
	v_pk_add_f32 v[126:127], v[126:127], v[168:169]
	v_pk_add_f32 v[124:125], v[124:125], v[180:181]
	v_pk_add_f32 v[118:119], v[118:119], v[174:175]
	v_pk_add_f32 v[116:117], v[116:117], v[186:187]
	v_pk_add_f32 v[122:123], v[122:123], v[170:171]
	v_pk_add_f32 v[120:121], v[120:121], v[182:183]
	v_pk_add_f32 v[168:169], v[114:115], v[176:177]
	v_pk_add_f32 v[170:171], v[112:113], v[188:189]
	v_mul_f32_e32 v114, v125, v125
	v_mul_f32_e32 v115, v127, v127
	v_cvt_pk_bf16_f32 v112, v124, v125
	v_cvt_pk_bf16_f32 v113, v126, v127
	v_mul_f32_e32 v125, v117, v117
	v_mul_f32_e32 v127, v119, v119
	v_mul_f32_e32 v174, v121, v121
	v_mul_f32_e32 v176, v171, v171
	v_fmac_f32_e32 v114, v124, v124
	v_fmac_f32_e32 v115, v126, v126
	v_fmac_f32_e32 v125, v116, v116
	v_fmac_f32_e32 v127, v118, v118
	v_mul_f32_e32 v175, v123, v123
	v_mul_f32_e32 v177, v169, v169
	v_fmac_f32_e32 v174, v120, v120
	v_fmac_f32_e32 v176, v170, v170
	v_add_f32_e32 v114, v114, v115
	v_add_f32_e32 v115, v125, v127
	v_fmac_f32_e32 v175, v122, v122
	v_fmac_f32_e32 v177, v168, v168
	v_add_f32_e32 v114, v174, v114
	v_add_f32_e32 v115, v176, v115
	v_add_f32_e32 v114, v175, v114
	v_add_f32_e32 v115, v177, v115
	v_add_f32_e32 v124, v114, v115
	ds_bpermute_b32 v125, v167, v124
	v_cvt_pk_bf16_f32 v114, v120, v121
	v_cvt_pk_bf16_f32 v115, v122, v123
	global_store_dwordx4 v[178:179], v[112:115], off
	v_lshlrev_b32_e32 v122, 2, v173
	s_waitcnt lgkmcnt(0)
	v_add_f32_e32 v112, v124, v125
	ds_bpermute_b32 v113, v122, v112
	v_cvt_pk_bf16_f32 v114, v116, v117
	v_cvt_pk_bf16_f32 v115, v118, v119
	v_cvt_pk_bf16_f32 v116, v170, v171
	v_cvt_pk_bf16_f32 v117, v168, v169
	global_store_dwordx4 v[178:179], v[114:117], off offset:256
	s_and_saveexec_b64 s[20:21], s[6:7]
	s_cbranch_execz .LBB0_984
	v_lshl_add_u64 v[114:115], v[156:157], 2, s[72:73]
	s_waitcnt lgkmcnt(0)
	v_add_f32_e32 v112, v112, v113
	global_atomic_add_f32 v[114:115], v112, off
